# adaLN GEMV hand-scheduled: 32 weight loads always in flight instead of dribbles of 8 with vmcnt(0); on top of merge hook/epilogue load batching
# speedup vs baseline: 1.0217x; 1.0101x over previous
; #define LAS __attribute__((address_space(3)))
; __device__ __forceinline__ void ada_block(const Params& p, LAS unsigned char* lds, int blk, int tid) {
;     ...
;     const int w = tid >> 6, lane = tid & 63, n = blk * 64 + lane;
;     f32x4 a0 = {0.f, 0.f, 0.f, 0.f}, a1 = a0, a2 = a0, a3 = a0;
;     const float* wp = p.w_ada + (size_t)(w * 128) * 3072 + n;
; #pragma unroll 32
;     for (int kk = 0; kk < 128; ++kk) {
;         const float wv = __builtin_nontemporal_load(wp + (size_t)kk * 3072);
;         const LAS f32x4* cp = (const LAS f32x4*)(cs + (w * 128 + kk) * 16);
;         a0 += cp[0] * wv; a1 += cp[1] * wv; a2 += cp[2] * wv; a3 += cp[3] * wv;
;     }
.LBB0_39:
	v_mul_u32_u24_e32 v240, 0x60000, v1
	v_or_b32_e32 v241, s10, v0
	v_add_lshl_u32 v240, v240, v241, 2
	s_mov_b64 s[100:101], s[80:81]
	v_mov_b32_e32 v64, 0
	v_mov_b32_e32 v65, 0
	v_mov_b32_e32 v66, 0
	v_mov_b32_e32 v67, 0
	v_mov_b32_e32 v68, 0
	v_mov_b32_e32 v69, 0
	v_mov_b32_e32 v70, 0
	v_mov_b32_e32 v71, 0
	v_mov_b32_e32 v72, 0
	v_mov_b32_e32 v73, 0
	v_mov_b32_e32 v74, 0
	v_mov_b32_e32 v75, 0
	v_mov_b32_e32 v76, 0
	v_mov_b32_e32 v77, 0
	v_mov_b32_e32 v78, 0
	v_mov_b32_e32 v79, 0
	global_load_dword v80, v240, s[100:101] nt
	s_add_u32 s100, s100, 0x3000
	s_addc_u32 s101, s101, 0
	global_load_dword v82, v240, s[100:101] nt
	s_add_u32 s100, s100, 0x3000
	s_addc_u32 s101, s101, 0
	global_load_dword v84, v240, s[100:101] nt
	s_add_u32 s100, s100, 0x3000
	s_addc_u32 s101, s101, 0
	global_load_dword v86, v240, s[100:101] nt
	s_add_u32 s100, s100, 0x3000
	s_addc_u32 s101, s101, 0
	global_load_dword v88, v240, s[100:101] nt
	s_add_u32 s100, s100, 0x3000
	s_addc_u32 s101, s101, 0
	global_load_dword v90, v240, s[100:101] nt
	s_add_u32 s100, s100, 0x3000
	s_addc_u32 s101, s101, 0
	global_load_dword v92, v240, s[100:101] nt
	s_add_u32 s100, s100, 0x3000
	s_addc_u32 s101, s101, 0
	global_load_dword v94, v240, s[100:101] nt
	s_add_u32 s100, s100, 0x3000
	s_addc_u32 s101, s101, 0
	global_load_dword v96, v240, s[100:101] nt
	s_add_u32 s100, s100, 0x3000
	s_addc_u32 s101, s101, 0
	global_load_dword v98, v240, s[100:101] nt
	s_add_u32 s100, s100, 0x3000
	s_addc_u32 s101, s101, 0
	global_load_dword v100, v240, s[100:101] nt
	s_add_u32 s100, s100, 0x3000
	s_addc_u32 s101, s101, 0
	global_load_dword v102, v240, s[100:101] nt
	s_add_u32 s100, s100, 0x3000
	s_addc_u32 s101, s101, 0
	global_load_dword v104, v240, s[100:101] nt
	s_add_u32 s100, s100, 0x3000
	s_addc_u32 s101, s101, 0
	global_load_dword v106, v240, s[100:101] nt
	s_add_u32 s100, s100, 0x3000
	s_addc_u32 s101, s101, 0
	global_load_dword v108, v240, s[100:101] nt
	s_add_u32 s100, s100, 0x3000
	s_addc_u32 s101, s101, 0
	global_load_dword v110, v240, s[100:101] nt
	s_add_u32 s100, s100, 0x3000
	s_addc_u32 s101, s101, 0
	global_load_dword v112, v240, s[100:101] nt
	s_add_u32 s100, s100, 0x3000
	s_addc_u32 s101, s101, 0
	global_load_dword v114, v240, s[100:101] nt
	s_add_u32 s100, s100, 0x3000
	s_addc_u32 s101, s101, 0
	global_load_dword v116, v240, s[100:101] nt
	s_add_u32 s100, s100, 0x3000
	s_addc_u32 s101, s101, 0
	global_load_dword v118, v240, s[100:101] nt
	s_add_u32 s100, s100, 0x3000
	s_addc_u32 s101, s101, 0
	global_load_dword v120, v240, s[100:101] nt
	s_add_u32 s100, s100, 0x3000
	s_addc_u32 s101, s101, 0
	global_load_dword v122, v240, s[100:101] nt
	s_add_u32 s100, s100, 0x3000
	s_addc_u32 s101, s101, 0
	global_load_dword v124, v240, s[100:101] nt
	s_add_u32 s100, s100, 0x3000
	s_addc_u32 s101, s101, 0
	global_load_dword v126, v240, s[100:101] nt
	s_add_u32 s100, s100, 0x3000
	s_addc_u32 s101, s101, 0
	global_load_dword v128, v240, s[100:101] nt
	s_add_u32 s100, s100, 0x3000
	s_addc_u32 s101, s101, 0
	global_load_dword v130, v240, s[100:101] nt
	s_add_u32 s100, s100, 0x3000
	s_addc_u32 s101, s101, 0
	global_load_dword v132, v240, s[100:101] nt
	s_add_u32 s100, s100, 0x3000
	s_addc_u32 s101, s101, 0
	global_load_dword v134, v240, s[100:101] nt
	s_add_u32 s100, s100, 0x3000
	s_addc_u32 s101, s101, 0
	global_load_dword v136, v240, s[100:101] nt
	s_add_u32 s100, s100, 0x3000
	s_addc_u32 s101, s101, 0
	global_load_dword v138, v240, s[100:101] nt
	s_add_u32 s100, s100, 0x3000
	s_addc_u32 s101, s101, 0
	global_load_dword v140, v240, s[100:101] nt
	s_add_u32 s100, s100, 0x3000
	s_addc_u32 s101, s101, 0
	global_load_dword v142, v240, s[100:101] nt
	s_add_u32 s100, s100, 0x3000
	s_addc_u32 s101, s101, 0
	ds_read_b128 v[176:179], v9 offset:0
	ds_read_b128 v[180:183], v9 offset:16
	ds_read_b128 v[184:187], v9 offset:32
	ds_read_b128 v[188:191], v9 offset:48
	ds_read_b128 v[192:195], v9 offset:64
	ds_read_b128 v[196:199], v9 offset:80
	ds_read_b128 v[200:203], v9 offset:96
	ds_read_b128 v[204:207], v9 offset:112
	ds_read_b128 v[208:211], v9 offset:128
	ds_read_b128 v[212:215], v9 offset:144
	ds_read_b128 v[216:219], v9 offset:160
	ds_read_b128 v[220:223], v9 offset:176
	s_waitcnt vmcnt(31) lgkmcnt(8)
	v_pk_fma_f32 v[64:65], v[176:177], v[80:81], v[64:65] op_sel_hi:[1,0,1]
	v_pk_fma_f32 v[66:67], v[178:179], v[80:81], v[66:67] op_sel_hi:[1,0,1]
	v_pk_fma_f32 v[68:69], v[180:181], v[80:81], v[68:69] op_sel_hi:[1,0,1]
	v_pk_fma_f32 v[70:71], v[182:183], v[80:81], v[70:71] op_sel_hi:[1,0,1]
	v_pk_fma_f32 v[72:73], v[184:185], v[80:81], v[72:73] op_sel_hi:[1,0,1]
	v_pk_fma_f32 v[74:75], v[186:187], v[80:81], v[74:75] op_sel_hi:[1,0,1]
	v_pk_fma_f32 v[76:77], v[188:189], v[80:81], v[76:77] op_sel_hi:[1,0,1]
	v_pk_fma_f32 v[78:79], v[190:191], v[80:81], v[78:79] op_sel_hi:[1,0,1]
	global_load_dword v80, v240, s[100:101] nt
	s_add_u32 s100, s100, 0x3000
	s_addc_u32 s101, s101, 0
	ds_read_b128 v[224:227], v9 offset:192
	ds_read_b128 v[228:231], v9 offset:208
	ds_read_b128 v[232:235], v9 offset:224
	ds_read_b128 v[236:239], v9 offset:240
	s_waitcnt vmcnt(31) lgkmcnt(8)
	v_pk_fma_f32 v[64:65], v[192:193], v[82:83], v[64:65] op_sel_hi:[1,0,1]
	v_pk_fma_f32 v[66:67], v[194:195], v[82:83], v[66:67] op_sel_hi:[1,0,1]
	v_pk_fma_f32 v[68:69], v[196:197], v[82:83], v[68:69] op_sel_hi:[1,0,1]
	v_pk_fma_f32 v[70:71], v[198:199], v[82:83], v[70:71] op_sel_hi:[1,0,1]
	v_pk_fma_f32 v[72:73], v[200:201], v[82:83], v[72:73] op_sel_hi:[1,0,1]
	v_pk_fma_f32 v[74:75], v[202:203], v[82:83], v[74:75] op_sel_hi:[1,0,1]
	v_pk_fma_f32 v[76:77], v[204:205], v[82:83], v[76:77] op_sel_hi:[1,0,1]
	v_pk_fma_f32 v[78:79], v[206:207], v[82:83], v[78:79] op_sel_hi:[1,0,1]
	global_load_dword v82, v240, s[100:101] nt
	s_add_u32 s100, s100, 0x3000
	s_addc_u32 s101, s101, 0
	ds_read_b128 v[176:179], v9 offset:256
	ds_read_b128 v[180:183], v9 offset:272
	ds_read_b128 v[184:187], v9 offset:288
	ds_read_b128 v[188:191], v9 offset:304
	s_waitcnt vmcnt(31) lgkmcnt(8)
; #define LAS __attribute__((address_space(3)))
; __device__ __forceinline__ void ada_block(const Params& p, LAS unsigned char* lds, int blk, int tid) {
;     ...
;     for (int kk = 0; kk < 128; ++kk) {
;         const float wv = __builtin_nontemporal_load(wp + (size_t)kk * 3072);
;         const LAS f32x4* cp = (const LAS f32x4*)(cs + (w * 128 + kk) * 16);
;         a0 += cp[0] * wv; a1 += cp[1] * wv; a2 += cp[2] * wv; a3 += cp[3] * wv;
;     }
	v_pk_fma_f32 v[64:65], v[208:209], v[84:85], v[64:65] op_sel_hi:[1,0,1]
	v_pk_fma_f32 v[66:67], v[210:211], v[84:85], v[66:67] op_sel_hi:[1,0,1]
	v_pk_fma_f32 v[68:69], v[212:213], v[84:85], v[68:69] op_sel_hi:[1,0,1]
	v_pk_fma_f32 v[70:71], v[214:215], v[84:85], v[70:71] op_sel_hi:[1,0,1]
	v_pk_fma_f32 v[72:73], v[216:217], v[84:85], v[72:73] op_sel_hi:[1,0,1]
	v_pk_fma_f32 v[74:75], v[218:219], v[84:85], v[74:75] op_sel_hi:[1,0,1]
	v_pk_fma_f32 v[76:77], v[220:221], v[84:85], v[76:77] op_sel_hi:[1,0,1]
	v_pk_fma_f32 v[78:79], v[222:223], v[84:85], v[78:79] op_sel_hi:[1,0,1]
	global_load_dword v84, v240, s[100:101] nt
	s_add_u32 s100, s100, 0x3000
	s_addc_u32 s101, s101, 0
	ds_read_b128 v[192:195], v9 offset:320
	ds_read_b128 v[196:199], v9 offset:336
	ds_read_b128 v[200:203], v9 offset:352
	ds_read_b128 v[204:207], v9 offset:368
	s_waitcnt vmcnt(31) lgkmcnt(8)
	v_pk_fma_f32 v[64:65], v[224:225], v[86:87], v[64:65] op_sel_hi:[1,0,1]
	v_pk_fma_f32 v[66:67], v[226:227], v[86:87], v[66:67] op_sel_hi:[1,0,1]
	v_pk_fma_f32 v[68:69], v[228:229], v[86:87], v[68:69] op_sel_hi:[1,0,1]
	v_pk_fma_f32 v[70:71], v[230:231], v[86:87], v[70:71] op_sel_hi:[1,0,1]
	v_pk_fma_f32 v[72:73], v[232:233], v[86:87], v[72:73] op_sel_hi:[1,0,1]
	v_pk_fma_f32 v[74:75], v[234:235], v[86:87], v[74:75] op_sel_hi:[1,0,1]
	v_pk_fma_f32 v[76:77], v[236:237], v[86:87], v[76:77] op_sel_hi:[1,0,1]
	v_pk_fma_f32 v[78:79], v[238:239], v[86:87], v[78:79] op_sel_hi:[1,0,1]
	global_load_dword v86, v240, s[100:101] nt
	s_add_u32 s100, s100, 0x3000
	s_addc_u32 s101, s101, 0
	ds_read_b128 v[208:211], v9 offset:384
	ds_read_b128 v[212:215], v9 offset:400
	ds_read_b128 v[216:219], v9 offset:416
	ds_read_b128 v[220:223], v9 offset:432
	s_waitcnt vmcnt(31) lgkmcnt(8)
	v_pk_fma_f32 v[64:65], v[176:177], v[88:89], v[64:65] op_sel_hi:[1,0,1]
	v_pk_fma_f32 v[66:67], v[178:179], v[88:89], v[66:67] op_sel_hi:[1,0,1]
	v_pk_fma_f32 v[68:69], v[180:181], v[88:89], v[68:69] op_sel_hi:[1,0,1]
	v_pk_fma_f32 v[70:71], v[182:183], v[88:89], v[70:71] op_sel_hi:[1,0,1]
	v_pk_fma_f32 v[72:73], v[184:185], v[88:89], v[72:73] op_sel_hi:[1,0,1]
	v_pk_fma_f32 v[74:75], v[186:187], v[88:89], v[74:75] op_sel_hi:[1,0,1]
	v_pk_fma_f32 v[76:77], v[188:189], v[88:89], v[76:77] op_sel_hi:[1,0,1]
	v_pk_fma_f32 v[78:79], v[190:191], v[88:89], v[78:79] op_sel_hi:[1,0,1]
	global_load_dword v88, v240, s[100:101] nt
	s_add_u32 s100, s100, 0x3000
	s_addc_u32 s101, s101, 0
	ds_read_b128 v[224:227], v9 offset:448
	ds_read_b128 v[228:231], v9 offset:464
	ds_read_b128 v[232:235], v9 offset:480
	ds_read_b128 v[236:239], v9 offset:496
	s_waitcnt vmcnt(31) lgkmcnt(8)
	v_pk_fma_f32 v[64:65], v[192:193], v[90:91], v[64:65] op_sel_hi:[1,0,1]
	v_pk_fma_f32 v[66:67], v[194:195], v[90:91], v[66:67] op_sel_hi:[1,0,1]
	v_pk_fma_f32 v[68:69], v[196:197], v[90:91], v[68:69] op_sel_hi:[1,0,1]
	v_pk_fma_f32 v[70:71], v[198:199], v[90:91], v[70:71] op_sel_hi:[1,0,1]
	v_pk_fma_f32 v[72:73], v[200:201], v[90:91], v[72:73] op_sel_hi:[1,0,1]
	v_pk_fma_f32 v[74:75], v[202:203], v[90:91], v[74:75] op_sel_hi:[1,0,1]
	v_pk_fma_f32 v[76:77], v[204:205], v[90:91], v[76:77] op_sel_hi:[1,0,1]
	v_pk_fma_f32 v[78:79], v[206:207], v[90:91], v[78:79] op_sel_hi:[1,0,1]
	global_load_dword v90, v240, s[100:101] nt
	s_add_u32 s100, s100, 0x3000
	s_addc_u32 s101, s101, 0
	ds_read_b128 v[176:179], v9 offset:512
	ds_read_b128 v[180:183], v9 offset:528
	ds_read_b128 v[184:187], v9 offset:544
	ds_read_b128 v[188:191], v9 offset:560
	s_waitcnt vmcnt(31) lgkmcnt(8)
	v_pk_fma_f32 v[64:65], v[208:209], v[92:93], v[64:65] op_sel_hi:[1,0,1]
	v_pk_fma_f32 v[66:67], v[210:211], v[92:93], v[66:67] op_sel_hi:[1,0,1]
	v_pk_fma_f32 v[68:69], v[212:213], v[92:93], v[68:69] op_sel_hi:[1,0,1]
	v_pk_fma_f32 v[70:71], v[214:215], v[92:93], v[70:71] op_sel_hi:[1,0,1]
	v_pk_fma_f32 v[72:73], v[216:217], v[92:93], v[72:73] op_sel_hi:[1,0,1]
	v_pk_fma_f32 v[74:75], v[218:219], v[92:93], v[74:75] op_sel_hi:[1,0,1]
	v_pk_fma_f32 v[76:77], v[220:221], v[92:93], v[76:77] op_sel_hi:[1,0,1]
	v_pk_fma_f32 v[78:79], v[222:223], v[92:93], v[78:79] op_sel_hi:[1,0,1]
	global_load_dword v92, v240, s[100:101] nt
	s_add_u32 s100, s100, 0x3000
	s_addc_u32 s101, s101, 0
	ds_read_b128 v[192:195], v9 offset:576
	ds_read_b128 v[196:199], v9 offset:592
	ds_read_b128 v[200:203], v9 offset:608
	ds_read_b128 v[204:207], v9 offset:624
	s_waitcnt vmcnt(31) lgkmcnt(8)
	v_pk_fma_f32 v[64:65], v[224:225], v[94:95], v[64:65] op_sel_hi:[1,0,1]
	v_pk_fma_f32 v[66:67], v[226:227], v[94:95], v[66:67] op_sel_hi:[1,0,1]
	v_pk_fma_f32 v[68:69], v[228:229], v[94:95], v[68:69] op_sel_hi:[1,0,1]
	v_pk_fma_f32 v[70:71], v[230:231], v[94:95], v[70:71] op_sel_hi:[1,0,1]
	v_pk_fma_f32 v[72:73], v[232:233], v[94:95], v[72:73] op_sel_hi:[1,0,1]
	v_pk_fma_f32 v[74:75], v[234:235], v[94:95], v[74:75] op_sel_hi:[1,0,1]
	v_pk_fma_f32 v[76:77], v[236:237], v[94:95], v[76:77] op_sel_hi:[1,0,1]
	v_pk_fma_f32 v[78:79], v[238:239], v[94:95], v[78:79] op_sel_hi:[1,0,1]
	global_load_dword v94, v240, s[100:101] nt
	s_add_u32 s100, s100, 0x3000
	s_addc_u32 s101, s101, 0
	ds_read_b128 v[208:211], v9 offset:640
	ds_read_b128 v[212:215], v9 offset:656
	ds_read_b128 v[216:219], v9 offset:672
	ds_read_b128 v[220:223], v9 offset:688
	s_waitcnt vmcnt(31) lgkmcnt(8)
; #define LAS __attribute__((address_space(3)))
; __device__ __forceinline__ void ada_block(const Params& p, LAS unsigned char* lds, int blk, int tid) {
;     ...
;     for (int kk = 0; kk < 128; ++kk) {
;         const float wv = __builtin_nontemporal_load(wp + (size_t)kk * 3072);
;         const LAS f32x4* cp = (const LAS f32x4*)(cs + (w * 128 + kk) * 16);
;         a0 += cp[0] * wv; a1 += cp[1] * wv; a2 += cp[2] * wv; a3 += cp[3] * wv;
;     }
	v_pk_fma_f32 v[64:65], v[176:177], v[96:97], v[64:65] op_sel_hi:[1,0,1]
	v_pk_fma_f32 v[66:67], v[178:179], v[96:97], v[66:67] op_sel_hi:[1,0,1]
	v_pk_fma_f32 v[68:69], v[180:181], v[96:97], v[68:69] op_sel_hi:[1,0,1]
	v_pk_fma_f32 v[70:71], v[182:183], v[96:97], v[70:71] op_sel_hi:[1,0,1]
	v_pk_fma_f32 v[72:73], v[184:185], v[96:97], v[72:73] op_sel_hi:[1,0,1]
	v_pk_fma_f32 v[74:75], v[186:187], v[96:97], v[74:75] op_sel_hi:[1,0,1]
	v_pk_fma_f32 v[76:77], v[188:189], v[96:97], v[76:77] op_sel_hi:[1,0,1]
	v_pk_fma_f32 v[78:79], v[190:191], v[96:97], v[78:79] op_sel_hi:[1,0,1]
	global_load_dword v96, v240, s[100:101] nt
	s_add_u32 s100, s100, 0x3000
	s_addc_u32 s101, s101, 0
	ds_read_b128 v[224:227], v9 offset:704
	ds_read_b128 v[228:231], v9 offset:720
	ds_read_b128 v[232:235], v9 offset:736
	ds_read_b128 v[236:239], v9 offset:752
	s_waitcnt vmcnt(31) lgkmcnt(8)
	v_pk_fma_f32 v[64:65], v[192:193], v[98:99], v[64:65] op_sel_hi:[1,0,1]
	v_pk_fma_f32 v[66:67], v[194:195], v[98:99], v[66:67] op_sel_hi:[1,0,1]
	v_pk_fma_f32 v[68:69], v[196:197], v[98:99], v[68:69] op_sel_hi:[1,0,1]
	v_pk_fma_f32 v[70:71], v[198:199], v[98:99], v[70:71] op_sel_hi:[1,0,1]
	v_pk_fma_f32 v[72:73], v[200:201], v[98:99], v[72:73] op_sel_hi:[1,0,1]
	v_pk_fma_f32 v[74:75], v[202:203], v[98:99], v[74:75] op_sel_hi:[1,0,1]
	v_pk_fma_f32 v[76:77], v[204:205], v[98:99], v[76:77] op_sel_hi:[1,0,1]
	v_pk_fma_f32 v[78:79], v[206:207], v[98:99], v[78:79] op_sel_hi:[1,0,1]
	global_load_dword v98, v240, s[100:101] nt
	s_add_u32 s100, s100, 0x3000
	s_addc_u32 s101, s101, 0
	ds_read_b128 v[176:179], v9 offset:768
	ds_read_b128 v[180:183], v9 offset:784
	ds_read_b128 v[184:187], v9 offset:800
	ds_read_b128 v[188:191], v9 offset:816
	s_waitcnt vmcnt(31) lgkmcnt(8)
	v_pk_fma_f32 v[64:65], v[208:209], v[100:101], v[64:65] op_sel_hi:[1,0,1]
	v_pk_fma_f32 v[66:67], v[210:211], v[100:101], v[66:67] op_sel_hi:[1,0,1]
	v_pk_fma_f32 v[68:69], v[212:213], v[100:101], v[68:69] op_sel_hi:[1,0,1]
	v_pk_fma_f32 v[70:71], v[214:215], v[100:101], v[70:71] op_sel_hi:[1,0,1]
	v_pk_fma_f32 v[72:73], v[216:217], v[100:101], v[72:73] op_sel_hi:[1,0,1]
	v_pk_fma_f32 v[74:75], v[218:219], v[100:101], v[74:75] op_sel_hi:[1,0,1]
	v_pk_fma_f32 v[76:77], v[220:221], v[100:101], v[76:77] op_sel_hi:[1,0,1]
	v_pk_fma_f32 v[78:79], v[222:223], v[100:101], v[78:79] op_sel_hi:[1,0,1]
	global_load_dword v100, v240, s[100:101] nt
	s_add_u32 s100, s100, 0x3000
	s_addc_u32 s101, s101, 0
	ds_read_b128 v[192:195], v9 offset:832
	ds_read_b128 v[196:199], v9 offset:848
	ds_read_b128 v[200:203], v9 offset:864
	ds_read_b128 v[204:207], v9 offset:880
	s_waitcnt vmcnt(31) lgkmcnt(8)
	v_pk_fma_f32 v[64:65], v[224:225], v[102:103], v[64:65] op_sel_hi:[1,0,1]
	v_pk_fma_f32 v[66:67], v[226:227], v[102:103], v[66:67] op_sel_hi:[1,0,1]
	v_pk_fma_f32 v[68:69], v[228:229], v[102:103], v[68:69] op_sel_hi:[1,0,1]
	v_pk_fma_f32 v[70:71], v[230:231], v[102:103], v[70:71] op_sel_hi:[1,0,1]
	v_pk_fma_f32 v[72:73], v[232:233], v[102:103], v[72:73] op_sel_hi:[1,0,1]
	v_pk_fma_f32 v[74:75], v[234:235], v[102:103], v[74:75] op_sel_hi:[1,0,1]
	v_pk_fma_f32 v[76:77], v[236:237], v[102:103], v[76:77] op_sel_hi:[1,0,1]
	v_pk_fma_f32 v[78:79], v[238:239], v[102:103], v[78:79] op_sel_hi:[1,0,1]
	global_load_dword v102, v240, s[100:101] nt
	s_add_u32 s100, s100, 0x3000
	s_addc_u32 s101, s101, 0
	ds_read_b128 v[208:211], v9 offset:896
	ds_read_b128 v[212:215], v9 offset:912
	ds_read_b128 v[216:219], v9 offset:928
	ds_read_b128 v[220:223], v9 offset:944
	s_waitcnt vmcnt(31) lgkmcnt(8)
	v_pk_fma_f32 v[64:65], v[176:177], v[104:105], v[64:65] op_sel_hi:[1,0,1]
	v_pk_fma_f32 v[66:67], v[178:179], v[104:105], v[66:67] op_sel_hi:[1,0,1]
	v_pk_fma_f32 v[68:69], v[180:181], v[104:105], v[68:69] op_sel_hi:[1,0,1]
	v_pk_fma_f32 v[70:71], v[182:183], v[104:105], v[70:71] op_sel_hi:[1,0,1]
	v_pk_fma_f32 v[72:73], v[184:185], v[104:105], v[72:73] op_sel_hi:[1,0,1]
	v_pk_fma_f32 v[74:75], v[186:187], v[104:105], v[74:75] op_sel_hi:[1,0,1]
	v_pk_fma_f32 v[76:77], v[188:189], v[104:105], v[76:77] op_sel_hi:[1,0,1]
	v_pk_fma_f32 v[78:79], v[190:191], v[104:105], v[78:79] op_sel_hi:[1,0,1]
	global_load_dword v104, v240, s[100:101] nt
	s_add_u32 s100, s100, 0x3000
	s_addc_u32 s101, s101, 0
	ds_read_b128 v[224:227], v9 offset:960
	ds_read_b128 v[228:231], v9 offset:976
	ds_read_b128 v[232:235], v9 offset:992
	ds_read_b128 v[236:239], v9 offset:1008
	s_waitcnt vmcnt(31) lgkmcnt(8)
	v_pk_fma_f32 v[64:65], v[192:193], v[106:107], v[64:65] op_sel_hi:[1,0,1]
	v_pk_fma_f32 v[66:67], v[194:195], v[106:107], v[66:67] op_sel_hi:[1,0,1]
	v_pk_fma_f32 v[68:69], v[196:197], v[106:107], v[68:69] op_sel_hi:[1,0,1]
	v_pk_fma_f32 v[70:71], v[198:199], v[106:107], v[70:71] op_sel_hi:[1,0,1]
	v_pk_fma_f32 v[72:73], v[200:201], v[106:107], v[72:73] op_sel_hi:[1,0,1]
	v_pk_fma_f32 v[74:75], v[202:203], v[106:107], v[74:75] op_sel_hi:[1,0,1]
	v_pk_fma_f32 v[76:77], v[204:205], v[106:107], v[76:77] op_sel_hi:[1,0,1]
	v_pk_fma_f32 v[78:79], v[206:207], v[106:107], v[78:79] op_sel_hi:[1,0,1]
	global_load_dword v106, v240, s[100:101] nt
	s_add_u32 s100, s100, 0x3000
	s_addc_u32 s101, s101, 0
	ds_read_b128 v[176:179], v9 offset:1024
	ds_read_b128 v[180:183], v9 offset:1040
	ds_read_b128 v[184:187], v9 offset:1056
	ds_read_b128 v[188:191], v9 offset:1072
	s_waitcnt vmcnt(31) lgkmcnt(8)
; #define LAS __attribute__((address_space(3)))
; __device__ __forceinline__ void ada_block(const Params& p, LAS unsigned char* lds, int blk, int tid) {
;     ...
;     for (int kk = 0; kk < 128; ++kk) {
;         const float wv = __builtin_nontemporal_load(wp + (size_t)kk * 3072);
;         const LAS f32x4* cp = (const LAS f32x4*)(cs + (w * 128 + kk) * 16);
;         a0 += cp[0] * wv; a1 += cp[1] * wv; a2 += cp[2] * wv; a3 += cp[3] * wv;
;     }
	v_pk_fma_f32 v[64:65], v[208:209], v[108:109], v[64:65] op_sel_hi:[1,0,1]
	v_pk_fma_f32 v[66:67], v[210:211], v[108:109], v[66:67] op_sel_hi:[1,0,1]
	v_pk_fma_f32 v[68:69], v[212:213], v[108:109], v[68:69] op_sel_hi:[1,0,1]
	v_pk_fma_f32 v[70:71], v[214:215], v[108:109], v[70:71] op_sel_hi:[1,0,1]
	v_pk_fma_f32 v[72:73], v[216:217], v[108:109], v[72:73] op_sel_hi:[1,0,1]
	v_pk_fma_f32 v[74:75], v[218:219], v[108:109], v[74:75] op_sel_hi:[1,0,1]
	v_pk_fma_f32 v[76:77], v[220:221], v[108:109], v[76:77] op_sel_hi:[1,0,1]
	v_pk_fma_f32 v[78:79], v[222:223], v[108:109], v[78:79] op_sel_hi:[1,0,1]
	global_load_dword v108, v240, s[100:101] nt
	s_add_u32 s100, s100, 0x3000
	s_addc_u32 s101, s101, 0
	ds_read_b128 v[192:195], v9 offset:1088
	ds_read_b128 v[196:199], v9 offset:1104
	ds_read_b128 v[200:203], v9 offset:1120
	ds_read_b128 v[204:207], v9 offset:1136
	s_waitcnt vmcnt(31) lgkmcnt(8)
	v_pk_fma_f32 v[64:65], v[224:225], v[110:111], v[64:65] op_sel_hi:[1,0,1]
	v_pk_fma_f32 v[66:67], v[226:227], v[110:111], v[66:67] op_sel_hi:[1,0,1]
	v_pk_fma_f32 v[68:69], v[228:229], v[110:111], v[68:69] op_sel_hi:[1,0,1]
	v_pk_fma_f32 v[70:71], v[230:231], v[110:111], v[70:71] op_sel_hi:[1,0,1]
	v_pk_fma_f32 v[72:73], v[232:233], v[110:111], v[72:73] op_sel_hi:[1,0,1]
	v_pk_fma_f32 v[74:75], v[234:235], v[110:111], v[74:75] op_sel_hi:[1,0,1]
	v_pk_fma_f32 v[76:77], v[236:237], v[110:111], v[76:77] op_sel_hi:[1,0,1]
	v_pk_fma_f32 v[78:79], v[238:239], v[110:111], v[78:79] op_sel_hi:[1,0,1]
	global_load_dword v110, v240, s[100:101] nt
	s_add_u32 s100, s100, 0x3000
	s_addc_u32 s101, s101, 0
	ds_read_b128 v[208:211], v9 offset:1152
	ds_read_b128 v[212:215], v9 offset:1168
	ds_read_b128 v[216:219], v9 offset:1184
	ds_read_b128 v[220:223], v9 offset:1200
	s_waitcnt vmcnt(31) lgkmcnt(8)
	v_pk_fma_f32 v[64:65], v[176:177], v[112:113], v[64:65] op_sel_hi:[1,0,1]
	v_pk_fma_f32 v[66:67], v[178:179], v[112:113], v[66:67] op_sel_hi:[1,0,1]
	v_pk_fma_f32 v[68:69], v[180:181], v[112:113], v[68:69] op_sel_hi:[1,0,1]
	v_pk_fma_f32 v[70:71], v[182:183], v[112:113], v[70:71] op_sel_hi:[1,0,1]
	v_pk_fma_f32 v[72:73], v[184:185], v[112:113], v[72:73] op_sel_hi:[1,0,1]
	v_pk_fma_f32 v[74:75], v[186:187], v[112:113], v[74:75] op_sel_hi:[1,0,1]
	v_pk_fma_f32 v[76:77], v[188:189], v[112:113], v[76:77] op_sel_hi:[1,0,1]
	v_pk_fma_f32 v[78:79], v[190:191], v[112:113], v[78:79] op_sel_hi:[1,0,1]
	global_load_dword v112, v240, s[100:101] nt
	s_add_u32 s100, s100, 0x3000
	s_addc_u32 s101, s101, 0
	ds_read_b128 v[224:227], v9 offset:1216
	ds_read_b128 v[228:231], v9 offset:1232
	ds_read_b128 v[232:235], v9 offset:1248
	ds_read_b128 v[236:239], v9 offset:1264
	s_waitcnt vmcnt(31) lgkmcnt(8)
	v_pk_fma_f32 v[64:65], v[192:193], v[114:115], v[64:65] op_sel_hi:[1,0,1]
	v_pk_fma_f32 v[66:67], v[194:195], v[114:115], v[66:67] op_sel_hi:[1,0,1]
	v_pk_fma_f32 v[68:69], v[196:197], v[114:115], v[68:69] op_sel_hi:[1,0,1]
	v_pk_fma_f32 v[70:71], v[198:199], v[114:115], v[70:71] op_sel_hi:[1,0,1]
	v_pk_fma_f32 v[72:73], v[200:201], v[114:115], v[72:73] op_sel_hi:[1,0,1]
	v_pk_fma_f32 v[74:75], v[202:203], v[114:115], v[74:75] op_sel_hi:[1,0,1]
	v_pk_fma_f32 v[76:77], v[204:205], v[114:115], v[76:77] op_sel_hi:[1,0,1]
	v_pk_fma_f32 v[78:79], v[206:207], v[114:115], v[78:79] op_sel_hi:[1,0,1]
	global_load_dword v114, v240, s[100:101] nt
	s_add_u32 s100, s100, 0x3000
	s_addc_u32 s101, s101, 0
	ds_read_b128 v[176:179], v9 offset:1280
	ds_read_b128 v[180:183], v9 offset:1296
	ds_read_b128 v[184:187], v9 offset:1312
	ds_read_b128 v[188:191], v9 offset:1328
	s_waitcnt vmcnt(31) lgkmcnt(8)
	v_pk_fma_f32 v[64:65], v[208:209], v[116:117], v[64:65] op_sel_hi:[1,0,1]
	v_pk_fma_f32 v[66:67], v[210:211], v[116:117], v[66:67] op_sel_hi:[1,0,1]
	v_pk_fma_f32 v[68:69], v[212:213], v[116:117], v[68:69] op_sel_hi:[1,0,1]
	v_pk_fma_f32 v[70:71], v[214:215], v[116:117], v[70:71] op_sel_hi:[1,0,1]
	v_pk_fma_f32 v[72:73], v[216:217], v[116:117], v[72:73] op_sel_hi:[1,0,1]
	v_pk_fma_f32 v[74:75], v[218:219], v[116:117], v[74:75] op_sel_hi:[1,0,1]
	v_pk_fma_f32 v[76:77], v[220:221], v[116:117], v[76:77] op_sel_hi:[1,0,1]
	v_pk_fma_f32 v[78:79], v[222:223], v[116:117], v[78:79] op_sel_hi:[1,0,1]
	global_load_dword v116, v240, s[100:101] nt
	s_add_u32 s100, s100, 0x3000
	s_addc_u32 s101, s101, 0
	ds_read_b128 v[192:195], v9 offset:1344
	ds_read_b128 v[196:199], v9 offset:1360
	ds_read_b128 v[200:203], v9 offset:1376
	ds_read_b128 v[204:207], v9 offset:1392
	s_waitcnt vmcnt(31) lgkmcnt(8)
	v_pk_fma_f32 v[64:65], v[224:225], v[118:119], v[64:65] op_sel_hi:[1,0,1]
	v_pk_fma_f32 v[66:67], v[226:227], v[118:119], v[66:67] op_sel_hi:[1,0,1]
	v_pk_fma_f32 v[68:69], v[228:229], v[118:119], v[68:69] op_sel_hi:[1,0,1]
	v_pk_fma_f32 v[70:71], v[230:231], v[118:119], v[70:71] op_sel_hi:[1,0,1]
	v_pk_fma_f32 v[72:73], v[232:233], v[118:119], v[72:73] op_sel_hi:[1,0,1]
	v_pk_fma_f32 v[74:75], v[234:235], v[118:119], v[74:75] op_sel_hi:[1,0,1]
	v_pk_fma_f32 v[76:77], v[236:237], v[118:119], v[76:77] op_sel_hi:[1,0,1]
	v_pk_fma_f32 v[78:79], v[238:239], v[118:119], v[78:79] op_sel_hi:[1,0,1]
	global_load_dword v118, v240, s[100:101] nt
	s_add_u32 s100, s100, 0x3000
	s_addc_u32 s101, s101, 0
	ds_read_b128 v[208:211], v9 offset:1408
	ds_read_b128 v[212:215], v9 offset:1424
	ds_read_b128 v[216:219], v9 offset:1440
	ds_read_b128 v[220:223], v9 offset:1456
	s_waitcnt vmcnt(31) lgkmcnt(8)
; #define LAS __attribute__((address_space(3)))
; __device__ __forceinline__ void ada_block(const Params& p, LAS unsigned char* lds, int blk, int tid) {
;     ...
;     for (int kk = 0; kk < 128; ++kk) {
;         const float wv = __builtin_nontemporal_load(wp + (size_t)kk * 3072);
;         const LAS f32x4* cp = (const LAS f32x4*)(cs + (w * 128 + kk) * 16);
;         a0 += cp[0] * wv; a1 += cp[1] * wv; a2 += cp[2] * wv; a3 += cp[3] * wv;
;     }
	v_pk_fma_f32 v[64:65], v[176:177], v[120:121], v[64:65] op_sel_hi:[1,0,1]
	v_pk_fma_f32 v[66:67], v[178:179], v[120:121], v[66:67] op_sel_hi:[1,0,1]
	v_pk_fma_f32 v[68:69], v[180:181], v[120:121], v[68:69] op_sel_hi:[1,0,1]
	v_pk_fma_f32 v[70:71], v[182:183], v[120:121], v[70:71] op_sel_hi:[1,0,1]
	v_pk_fma_f32 v[72:73], v[184:185], v[120:121], v[72:73] op_sel_hi:[1,0,1]
	v_pk_fma_f32 v[74:75], v[186:187], v[120:121], v[74:75] op_sel_hi:[1,0,1]
	v_pk_fma_f32 v[76:77], v[188:189], v[120:121], v[76:77] op_sel_hi:[1,0,1]
	v_pk_fma_f32 v[78:79], v[190:191], v[120:121], v[78:79] op_sel_hi:[1,0,1]
	global_load_dword v120, v240, s[100:101] nt
	s_add_u32 s100, s100, 0x3000
	s_addc_u32 s101, s101, 0
	ds_read_b128 v[224:227], v9 offset:1472
	ds_read_b128 v[228:231], v9 offset:1488
	ds_read_b128 v[232:235], v9 offset:1504
	ds_read_b128 v[236:239], v9 offset:1520
	s_waitcnt vmcnt(31) lgkmcnt(8)
	v_pk_fma_f32 v[64:65], v[192:193], v[122:123], v[64:65] op_sel_hi:[1,0,1]
	v_pk_fma_f32 v[66:67], v[194:195], v[122:123], v[66:67] op_sel_hi:[1,0,1]
	v_pk_fma_f32 v[68:69], v[196:197], v[122:123], v[68:69] op_sel_hi:[1,0,1]
	v_pk_fma_f32 v[70:71], v[198:199], v[122:123], v[70:71] op_sel_hi:[1,0,1]
	v_pk_fma_f32 v[72:73], v[200:201], v[122:123], v[72:73] op_sel_hi:[1,0,1]
	v_pk_fma_f32 v[74:75], v[202:203], v[122:123], v[74:75] op_sel_hi:[1,0,1]
	v_pk_fma_f32 v[76:77], v[204:205], v[122:123], v[76:77] op_sel_hi:[1,0,1]
	v_pk_fma_f32 v[78:79], v[206:207], v[122:123], v[78:79] op_sel_hi:[1,0,1]
	global_load_dword v122, v240, s[100:101] nt
	s_add_u32 s100, s100, 0x3000
	s_addc_u32 s101, s101, 0
	ds_read_b128 v[176:179], v9 offset:1536
	ds_read_b128 v[180:183], v9 offset:1552
	ds_read_b128 v[184:187], v9 offset:1568
	ds_read_b128 v[188:191], v9 offset:1584
	s_waitcnt vmcnt(31) lgkmcnt(8)
	v_pk_fma_f32 v[64:65], v[208:209], v[124:125], v[64:65] op_sel_hi:[1,0,1]
	v_pk_fma_f32 v[66:67], v[210:211], v[124:125], v[66:67] op_sel_hi:[1,0,1]
	v_pk_fma_f32 v[68:69], v[212:213], v[124:125], v[68:69] op_sel_hi:[1,0,1]
	v_pk_fma_f32 v[70:71], v[214:215], v[124:125], v[70:71] op_sel_hi:[1,0,1]
	v_pk_fma_f32 v[72:73], v[216:217], v[124:125], v[72:73] op_sel_hi:[1,0,1]
	v_pk_fma_f32 v[74:75], v[218:219], v[124:125], v[74:75] op_sel_hi:[1,0,1]
	v_pk_fma_f32 v[76:77], v[220:221], v[124:125], v[76:77] op_sel_hi:[1,0,1]
	v_pk_fma_f32 v[78:79], v[222:223], v[124:125], v[78:79] op_sel_hi:[1,0,1]
	global_load_dword v124, v240, s[100:101] nt
	s_add_u32 s100, s100, 0x3000
	s_addc_u32 s101, s101, 0
	ds_read_b128 v[192:195], v9 offset:1600
	ds_read_b128 v[196:199], v9 offset:1616
	ds_read_b128 v[200:203], v9 offset:1632
	ds_read_b128 v[204:207], v9 offset:1648
	s_waitcnt vmcnt(31) lgkmcnt(8)
	v_pk_fma_f32 v[64:65], v[224:225], v[126:127], v[64:65] op_sel_hi:[1,0,1]
	v_pk_fma_f32 v[66:67], v[226:227], v[126:127], v[66:67] op_sel_hi:[1,0,1]
	v_pk_fma_f32 v[68:69], v[228:229], v[126:127], v[68:69] op_sel_hi:[1,0,1]
	v_pk_fma_f32 v[70:71], v[230:231], v[126:127], v[70:71] op_sel_hi:[1,0,1]
	v_pk_fma_f32 v[72:73], v[232:233], v[126:127], v[72:73] op_sel_hi:[1,0,1]
	v_pk_fma_f32 v[74:75], v[234:235], v[126:127], v[74:75] op_sel_hi:[1,0,1]
	v_pk_fma_f32 v[76:77], v[236:237], v[126:127], v[76:77] op_sel_hi:[1,0,1]
	v_pk_fma_f32 v[78:79], v[238:239], v[126:127], v[78:79] op_sel_hi:[1,0,1]
	global_load_dword v126, v240, s[100:101] nt
	s_add_u32 s100, s100, 0x3000
	s_addc_u32 s101, s101, 0
	ds_read_b128 v[208:211], v9 offset:1664
	ds_read_b128 v[212:215], v9 offset:1680
	ds_read_b128 v[216:219], v9 offset:1696
	ds_read_b128 v[220:223], v9 offset:1712
	s_waitcnt vmcnt(31) lgkmcnt(8)
	v_pk_fma_f32 v[64:65], v[176:177], v[128:129], v[64:65] op_sel_hi:[1,0,1]
	v_pk_fma_f32 v[66:67], v[178:179], v[128:129], v[66:67] op_sel_hi:[1,0,1]
	v_pk_fma_f32 v[68:69], v[180:181], v[128:129], v[68:69] op_sel_hi:[1,0,1]
	v_pk_fma_f32 v[70:71], v[182:183], v[128:129], v[70:71] op_sel_hi:[1,0,1]
	v_pk_fma_f32 v[72:73], v[184:185], v[128:129], v[72:73] op_sel_hi:[1,0,1]
	v_pk_fma_f32 v[74:75], v[186:187], v[128:129], v[74:75] op_sel_hi:[1,0,1]
	v_pk_fma_f32 v[76:77], v[188:189], v[128:129], v[76:77] op_sel_hi:[1,0,1]
	v_pk_fma_f32 v[78:79], v[190:191], v[128:129], v[78:79] op_sel_hi:[1,0,1]
	global_load_dword v128, v240, s[100:101] nt
	s_add_u32 s100, s100, 0x3000
	s_addc_u32 s101, s101, 0
	ds_read_b128 v[224:227], v9 offset:1728
	ds_read_b128 v[228:231], v9 offset:1744
	ds_read_b128 v[232:235], v9 offset:1760
	ds_read_b128 v[236:239], v9 offset:1776
	s_waitcnt vmcnt(31) lgkmcnt(8)
	v_pk_fma_f32 v[64:65], v[192:193], v[130:131], v[64:65] op_sel_hi:[1,0,1]
	v_pk_fma_f32 v[66:67], v[194:195], v[130:131], v[66:67] op_sel_hi:[1,0,1]
	v_pk_fma_f32 v[68:69], v[196:197], v[130:131], v[68:69] op_sel_hi:[1,0,1]
	v_pk_fma_f32 v[70:71], v[198:199], v[130:131], v[70:71] op_sel_hi:[1,0,1]
	v_pk_fma_f32 v[72:73], v[200:201], v[130:131], v[72:73] op_sel_hi:[1,0,1]
	v_pk_fma_f32 v[74:75], v[202:203], v[130:131], v[74:75] op_sel_hi:[1,0,1]
	v_pk_fma_f32 v[76:77], v[204:205], v[130:131], v[76:77] op_sel_hi:[1,0,1]
	v_pk_fma_f32 v[78:79], v[206:207], v[130:131], v[78:79] op_sel_hi:[1,0,1]
	global_load_dword v130, v240, s[100:101] nt
	s_add_u32 s100, s100, 0x3000
	s_addc_u32 s101, s101, 0
	ds_read_b128 v[176:179], v9 offset:1792
	ds_read_b128 v[180:183], v9 offset:1808
	ds_read_b128 v[184:187], v9 offset:1824
	ds_read_b128 v[188:191], v9 offset:1840
	s_waitcnt vmcnt(31) lgkmcnt(8)
; #define LAS __attribute__((address_space(3)))
; __device__ __forceinline__ void ada_block(const Params& p, LAS unsigned char* lds, int blk, int tid) {
;     ...
;     for (int kk = 0; kk < 128; ++kk) {
;         const float wv = __builtin_nontemporal_load(wp + (size_t)kk * 3072);
;         const LAS f32x4* cp = (const LAS f32x4*)(cs + (w * 128 + kk) * 16);
;         a0 += cp[0] * wv; a1 += cp[1] * wv; a2 += cp[2] * wv; a3 += cp[3] * wv;
;     }
	v_pk_fma_f32 v[64:65], v[208:209], v[132:133], v[64:65] op_sel_hi:[1,0,1]
	v_pk_fma_f32 v[66:67], v[210:211], v[132:133], v[66:67] op_sel_hi:[1,0,1]
	v_pk_fma_f32 v[68:69], v[212:213], v[132:133], v[68:69] op_sel_hi:[1,0,1]
	v_pk_fma_f32 v[70:71], v[214:215], v[132:133], v[70:71] op_sel_hi:[1,0,1]
	v_pk_fma_f32 v[72:73], v[216:217], v[132:133], v[72:73] op_sel_hi:[1,0,1]
	v_pk_fma_f32 v[74:75], v[218:219], v[132:133], v[74:75] op_sel_hi:[1,0,1]
	v_pk_fma_f32 v[76:77], v[220:221], v[132:133], v[76:77] op_sel_hi:[1,0,1]
	v_pk_fma_f32 v[78:79], v[222:223], v[132:133], v[78:79] op_sel_hi:[1,0,1]
	global_load_dword v132, v240, s[100:101] nt
	s_add_u32 s100, s100, 0x3000
	s_addc_u32 s101, s101, 0
	ds_read_b128 v[192:195], v9 offset:1856
	ds_read_b128 v[196:199], v9 offset:1872
	ds_read_b128 v[200:203], v9 offset:1888
	ds_read_b128 v[204:207], v9 offset:1904
	s_waitcnt vmcnt(31) lgkmcnt(8)
	v_pk_fma_f32 v[64:65], v[224:225], v[134:135], v[64:65] op_sel_hi:[1,0,1]
	v_pk_fma_f32 v[66:67], v[226:227], v[134:135], v[66:67] op_sel_hi:[1,0,1]
	v_pk_fma_f32 v[68:69], v[228:229], v[134:135], v[68:69] op_sel_hi:[1,0,1]
	v_pk_fma_f32 v[70:71], v[230:231], v[134:135], v[70:71] op_sel_hi:[1,0,1]
	v_pk_fma_f32 v[72:73], v[232:233], v[134:135], v[72:73] op_sel_hi:[1,0,1]
	v_pk_fma_f32 v[74:75], v[234:235], v[134:135], v[74:75] op_sel_hi:[1,0,1]
	v_pk_fma_f32 v[76:77], v[236:237], v[134:135], v[76:77] op_sel_hi:[1,0,1]
	v_pk_fma_f32 v[78:79], v[238:239], v[134:135], v[78:79] op_sel_hi:[1,0,1]
	global_load_dword v134, v240, s[100:101] nt
	s_add_u32 s100, s100, 0x3000
	s_addc_u32 s101, s101, 0
	ds_read_b128 v[208:211], v9 offset:1920
	ds_read_b128 v[212:215], v9 offset:1936
	ds_read_b128 v[216:219], v9 offset:1952
	ds_read_b128 v[220:223], v9 offset:1968
	s_waitcnt vmcnt(31) lgkmcnt(8)
	v_pk_fma_f32 v[64:65], v[176:177], v[136:137], v[64:65] op_sel_hi:[1,0,1]
	v_pk_fma_f32 v[66:67], v[178:179], v[136:137], v[66:67] op_sel_hi:[1,0,1]
	v_pk_fma_f32 v[68:69], v[180:181], v[136:137], v[68:69] op_sel_hi:[1,0,1]
	v_pk_fma_f32 v[70:71], v[182:183], v[136:137], v[70:71] op_sel_hi:[1,0,1]
	v_pk_fma_f32 v[72:73], v[184:185], v[136:137], v[72:73] op_sel_hi:[1,0,1]
	v_pk_fma_f32 v[74:75], v[186:187], v[136:137], v[74:75] op_sel_hi:[1,0,1]
	v_pk_fma_f32 v[76:77], v[188:189], v[136:137], v[76:77] op_sel_hi:[1,0,1]
	v_pk_fma_f32 v[78:79], v[190:191], v[136:137], v[78:79] op_sel_hi:[1,0,1]
	global_load_dword v136, v240, s[100:101] nt
	s_add_u32 s100, s100, 0x3000
	s_addc_u32 s101, s101, 0
	ds_read_b128 v[224:227], v9 offset:1984
	ds_read_b128 v[228:231], v9 offset:2000
	ds_read_b128 v[232:235], v9 offset:2016
	ds_read_b128 v[236:239], v9 offset:2032
	s_waitcnt vmcnt(31) lgkmcnt(8)
	v_pk_fma_f32 v[64:65], v[192:193], v[138:139], v[64:65] op_sel_hi:[1,0,1]
	v_pk_fma_f32 v[66:67], v[194:195], v[138:139], v[66:67] op_sel_hi:[1,0,1]
	v_pk_fma_f32 v[68:69], v[196:197], v[138:139], v[68:69] op_sel_hi:[1,0,1]
	v_pk_fma_f32 v[70:71], v[198:199], v[138:139], v[70:71] op_sel_hi:[1,0,1]
	v_pk_fma_f32 v[72:73], v[200:201], v[138:139], v[72:73] op_sel_hi:[1,0,1]
	v_pk_fma_f32 v[74:75], v[202:203], v[138:139], v[74:75] op_sel_hi:[1,0,1]
	v_pk_fma_f32 v[76:77], v[204:205], v[138:139], v[76:77] op_sel_hi:[1,0,1]
	v_pk_fma_f32 v[78:79], v[206:207], v[138:139], v[78:79] op_sel_hi:[1,0,1]
	global_load_dword v138, v240, s[100:101] nt
	s_add_u32 s100, s100, 0x3000
	s_addc_u32 s101, s101, 0
	ds_read_b128 v[176:179], v9 offset:2048
	ds_read_b128 v[180:183], v9 offset:2064
	ds_read_b128 v[184:187], v9 offset:2080
	ds_read_b128 v[188:191], v9 offset:2096
	s_waitcnt vmcnt(31) lgkmcnt(8)
	v_pk_fma_f32 v[64:65], v[208:209], v[140:141], v[64:65] op_sel_hi:[1,0,1]
	v_pk_fma_f32 v[66:67], v[210:211], v[140:141], v[66:67] op_sel_hi:[1,0,1]
	v_pk_fma_f32 v[68:69], v[212:213], v[140:141], v[68:69] op_sel_hi:[1,0,1]
	v_pk_fma_f32 v[70:71], v[214:215], v[140:141], v[70:71] op_sel_hi:[1,0,1]
	v_pk_fma_f32 v[72:73], v[216:217], v[140:141], v[72:73] op_sel_hi:[1,0,1]
	v_pk_fma_f32 v[74:75], v[218:219], v[140:141], v[74:75] op_sel_hi:[1,0,1]
	v_pk_fma_f32 v[76:77], v[220:221], v[140:141], v[76:77] op_sel_hi:[1,0,1]
	v_pk_fma_f32 v[78:79], v[222:223], v[140:141], v[78:79] op_sel_hi:[1,0,1]
	global_load_dword v140, v240, s[100:101] nt
	s_add_u32 s100, s100, 0x3000
	s_addc_u32 s101, s101, 0
	ds_read_b128 v[192:195], v9 offset:2112
	ds_read_b128 v[196:199], v9 offset:2128
	ds_read_b128 v[200:203], v9 offset:2144
	ds_read_b128 v[204:207], v9 offset:2160
	s_waitcnt vmcnt(31) lgkmcnt(8)
	v_pk_fma_f32 v[64:65], v[224:225], v[142:143], v[64:65] op_sel_hi:[1,0,1]
	v_pk_fma_f32 v[66:67], v[226:227], v[142:143], v[66:67] op_sel_hi:[1,0,1]
	v_pk_fma_f32 v[68:69], v[228:229], v[142:143], v[68:69] op_sel_hi:[1,0,1]
	v_pk_fma_f32 v[70:71], v[230:231], v[142:143], v[70:71] op_sel_hi:[1,0,1]
	v_pk_fma_f32 v[72:73], v[232:233], v[142:143], v[72:73] op_sel_hi:[1,0,1]
	v_pk_fma_f32 v[74:75], v[234:235], v[142:143], v[74:75] op_sel_hi:[1,0,1]
	v_pk_fma_f32 v[76:77], v[236:237], v[142:143], v[76:77] op_sel_hi:[1,0,1]
	v_pk_fma_f32 v[78:79], v[238:239], v[142:143], v[78:79] op_sel_hi:[1,0,1]
	global_load_dword v142, v240, s[100:101] nt
	s_add_u32 s100, s100, 0x3000
	s_addc_u32 s101, s101, 0
	ds_read_b128 v[208:211], v9 offset:2176
	ds_read_b128 v[212:215], v9 offset:2192
	ds_read_b128 v[216:219], v9 offset:2208
	ds_read_b128 v[220:223], v9 offset:2224
	s_waitcnt vmcnt(31) lgkmcnt(8)
; #define LAS __attribute__((address_space(3)))
; __device__ __forceinline__ void ada_block(const Params& p, LAS unsigned char* lds, int blk, int tid) {
;     ...
;     for (int kk = 0; kk < 128; ++kk) {
;         const float wv = __builtin_nontemporal_load(wp + (size_t)kk * 3072);
;         const LAS f32x4* cp = (const LAS f32x4*)(cs + (w * 128 + kk) * 16);
;         a0 += cp[0] * wv; a1 += cp[1] * wv; a2 += cp[2] * wv; a3 += cp[3] * wv;
;     }
	v_pk_fma_f32 v[64:65], v[176:177], v[80:81], v[64:65] op_sel_hi:[1,0,1]
	v_pk_fma_f32 v[66:67], v[178:179], v[80:81], v[66:67] op_sel_hi:[1,0,1]
	v_pk_fma_f32 v[68:69], v[180:181], v[80:81], v[68:69] op_sel_hi:[1,0,1]
	v_pk_fma_f32 v[70:71], v[182:183], v[80:81], v[70:71] op_sel_hi:[1,0,1]
	v_pk_fma_f32 v[72:73], v[184:185], v[80:81], v[72:73] op_sel_hi:[1,0,1]
	v_pk_fma_f32 v[74:75], v[186:187], v[80:81], v[74:75] op_sel_hi:[1,0,1]
	v_pk_fma_f32 v[76:77], v[188:189], v[80:81], v[76:77] op_sel_hi:[1,0,1]
	v_pk_fma_f32 v[78:79], v[190:191], v[80:81], v[78:79] op_sel_hi:[1,0,1]
	global_load_dword v80, v240, s[100:101] nt
	s_add_u32 s100, s100, 0x3000
	s_addc_u32 s101, s101, 0
	ds_read_b128 v[224:227], v9 offset:2240
	ds_read_b128 v[228:231], v9 offset:2256
	ds_read_b128 v[232:235], v9 offset:2272
	ds_read_b128 v[236:239], v9 offset:2288
	s_waitcnt vmcnt(31) lgkmcnt(8)
	v_pk_fma_f32 v[64:65], v[192:193], v[82:83], v[64:65] op_sel_hi:[1,0,1]
	v_pk_fma_f32 v[66:67], v[194:195], v[82:83], v[66:67] op_sel_hi:[1,0,1]
	v_pk_fma_f32 v[68:69], v[196:197], v[82:83], v[68:69] op_sel_hi:[1,0,1]
	v_pk_fma_f32 v[70:71], v[198:199], v[82:83], v[70:71] op_sel_hi:[1,0,1]
	v_pk_fma_f32 v[72:73], v[200:201], v[82:83], v[72:73] op_sel_hi:[1,0,1]
	v_pk_fma_f32 v[74:75], v[202:203], v[82:83], v[74:75] op_sel_hi:[1,0,1]
	v_pk_fma_f32 v[76:77], v[204:205], v[82:83], v[76:77] op_sel_hi:[1,0,1]
	v_pk_fma_f32 v[78:79], v[206:207], v[82:83], v[78:79] op_sel_hi:[1,0,1]
	global_load_dword v82, v240, s[100:101] nt
	s_add_u32 s100, s100, 0x3000
	s_addc_u32 s101, s101, 0
	ds_read_b128 v[176:179], v9 offset:2304
	ds_read_b128 v[180:183], v9 offset:2320
	ds_read_b128 v[184:187], v9 offset:2336
	ds_read_b128 v[188:191], v9 offset:2352
	s_waitcnt vmcnt(31) lgkmcnt(8)
	v_pk_fma_f32 v[64:65], v[208:209], v[84:85], v[64:65] op_sel_hi:[1,0,1]
	v_pk_fma_f32 v[66:67], v[210:211], v[84:85], v[66:67] op_sel_hi:[1,0,1]
	v_pk_fma_f32 v[68:69], v[212:213], v[84:85], v[68:69] op_sel_hi:[1,0,1]
	v_pk_fma_f32 v[70:71], v[214:215], v[84:85], v[70:71] op_sel_hi:[1,0,1]
	v_pk_fma_f32 v[72:73], v[216:217], v[84:85], v[72:73] op_sel_hi:[1,0,1]
	v_pk_fma_f32 v[74:75], v[218:219], v[84:85], v[74:75] op_sel_hi:[1,0,1]
	v_pk_fma_f32 v[76:77], v[220:221], v[84:85], v[76:77] op_sel_hi:[1,0,1]
	v_pk_fma_f32 v[78:79], v[222:223], v[84:85], v[78:79] op_sel_hi:[1,0,1]
	global_load_dword v84, v240, s[100:101] nt
	s_add_u32 s100, s100, 0x3000
	s_addc_u32 s101, s101, 0
	ds_read_b128 v[192:195], v9 offset:2368
	ds_read_b128 v[196:199], v9 offset:2384
	ds_read_b128 v[200:203], v9 offset:2400
	ds_read_b128 v[204:207], v9 offset:2416
	s_waitcnt vmcnt(31) lgkmcnt(8)
	v_pk_fma_f32 v[64:65], v[224:225], v[86:87], v[64:65] op_sel_hi:[1,0,1]
	v_pk_fma_f32 v[66:67], v[226:227], v[86:87], v[66:67] op_sel_hi:[1,0,1]
	v_pk_fma_f32 v[68:69], v[228:229], v[86:87], v[68:69] op_sel_hi:[1,0,1]
	v_pk_fma_f32 v[70:71], v[230:231], v[86:87], v[70:71] op_sel_hi:[1,0,1]
	v_pk_fma_f32 v[72:73], v[232:233], v[86:87], v[72:73] op_sel_hi:[1,0,1]
	v_pk_fma_f32 v[74:75], v[234:235], v[86:87], v[74:75] op_sel_hi:[1,0,1]
	v_pk_fma_f32 v[76:77], v[236:237], v[86:87], v[76:77] op_sel_hi:[1,0,1]
	v_pk_fma_f32 v[78:79], v[238:239], v[86:87], v[78:79] op_sel_hi:[1,0,1]
	global_load_dword v86, v240, s[100:101] nt
	s_add_u32 s100, s100, 0x3000
	s_addc_u32 s101, s101, 0
	ds_read_b128 v[208:211], v9 offset:2432
	ds_read_b128 v[212:215], v9 offset:2448
	ds_read_b128 v[216:219], v9 offset:2464
	ds_read_b128 v[220:223], v9 offset:2480
	s_waitcnt vmcnt(31) lgkmcnt(8)
	v_pk_fma_f32 v[64:65], v[176:177], v[88:89], v[64:65] op_sel_hi:[1,0,1]
	v_pk_fma_f32 v[66:67], v[178:179], v[88:89], v[66:67] op_sel_hi:[1,0,1]
	v_pk_fma_f32 v[68:69], v[180:181], v[88:89], v[68:69] op_sel_hi:[1,0,1]
	v_pk_fma_f32 v[70:71], v[182:183], v[88:89], v[70:71] op_sel_hi:[1,0,1]
	v_pk_fma_f32 v[72:73], v[184:185], v[88:89], v[72:73] op_sel_hi:[1,0,1]
	v_pk_fma_f32 v[74:75], v[186:187], v[88:89], v[74:75] op_sel_hi:[1,0,1]
	v_pk_fma_f32 v[76:77], v[188:189], v[88:89], v[76:77] op_sel_hi:[1,0,1]
	v_pk_fma_f32 v[78:79], v[190:191], v[88:89], v[78:79] op_sel_hi:[1,0,1]
	global_load_dword v88, v240, s[100:101] nt
	s_add_u32 s100, s100, 0x3000
	s_addc_u32 s101, s101, 0
	ds_read_b128 v[224:227], v9 offset:2496
	ds_read_b128 v[228:231], v9 offset:2512
	ds_read_b128 v[232:235], v9 offset:2528
	ds_read_b128 v[236:239], v9 offset:2544
	s_waitcnt vmcnt(31) lgkmcnt(8)
	v_pk_fma_f32 v[64:65], v[192:193], v[90:91], v[64:65] op_sel_hi:[1,0,1]
	v_pk_fma_f32 v[66:67], v[194:195], v[90:91], v[66:67] op_sel_hi:[1,0,1]
	v_pk_fma_f32 v[68:69], v[196:197], v[90:91], v[68:69] op_sel_hi:[1,0,1]
	v_pk_fma_f32 v[70:71], v[198:199], v[90:91], v[70:71] op_sel_hi:[1,0,1]
	v_pk_fma_f32 v[72:73], v[200:201], v[90:91], v[72:73] op_sel_hi:[1,0,1]
	v_pk_fma_f32 v[74:75], v[202:203], v[90:91], v[74:75] op_sel_hi:[1,0,1]
	v_pk_fma_f32 v[76:77], v[204:205], v[90:91], v[76:77] op_sel_hi:[1,0,1]
	v_pk_fma_f32 v[78:79], v[206:207], v[90:91], v[78:79] op_sel_hi:[1,0,1]
	global_load_dword v90, v240, s[100:101] nt
	s_add_u32 s100, s100, 0x3000
	s_addc_u32 s101, s101, 0
	ds_read_b128 v[176:179], v9 offset:2560
	ds_read_b128 v[180:183], v9 offset:2576
	ds_read_b128 v[184:187], v9 offset:2592
	ds_read_b128 v[188:191], v9 offset:2608
	s_waitcnt vmcnt(31) lgkmcnt(8)
; #define LAS __attribute__((address_space(3)))
; __device__ __forceinline__ void ada_block(const Params& p, LAS unsigned char* lds, int blk, int tid) {
;     ...
;     for (int kk = 0; kk < 128; ++kk) {
;         const float wv = __builtin_nontemporal_load(wp + (size_t)kk * 3072);
;         const LAS f32x4* cp = (const LAS f32x4*)(cs + (w * 128 + kk) * 16);
;         a0 += cp[0] * wv; a1 += cp[1] * wv; a2 += cp[2] * wv; a3 += cp[3] * wv;
;     }
	v_pk_fma_f32 v[64:65], v[208:209], v[92:93], v[64:65] op_sel_hi:[1,0,1]
	v_pk_fma_f32 v[66:67], v[210:211], v[92:93], v[66:67] op_sel_hi:[1,0,1]
	v_pk_fma_f32 v[68:69], v[212:213], v[92:93], v[68:69] op_sel_hi:[1,0,1]
	v_pk_fma_f32 v[70:71], v[214:215], v[92:93], v[70:71] op_sel_hi:[1,0,1]
	v_pk_fma_f32 v[72:73], v[216:217], v[92:93], v[72:73] op_sel_hi:[1,0,1]
	v_pk_fma_f32 v[74:75], v[218:219], v[92:93], v[74:75] op_sel_hi:[1,0,1]
	v_pk_fma_f32 v[76:77], v[220:221], v[92:93], v[76:77] op_sel_hi:[1,0,1]
	v_pk_fma_f32 v[78:79], v[222:223], v[92:93], v[78:79] op_sel_hi:[1,0,1]
	global_load_dword v92, v240, s[100:101] nt
	s_add_u32 s100, s100, 0x3000
	s_addc_u32 s101, s101, 0
	ds_read_b128 v[192:195], v9 offset:2624
	ds_read_b128 v[196:199], v9 offset:2640
	ds_read_b128 v[200:203], v9 offset:2656
	ds_read_b128 v[204:207], v9 offset:2672
	s_waitcnt vmcnt(31) lgkmcnt(8)
	v_pk_fma_f32 v[64:65], v[224:225], v[94:95], v[64:65] op_sel_hi:[1,0,1]
	v_pk_fma_f32 v[66:67], v[226:227], v[94:95], v[66:67] op_sel_hi:[1,0,1]
	v_pk_fma_f32 v[68:69], v[228:229], v[94:95], v[68:69] op_sel_hi:[1,0,1]
	v_pk_fma_f32 v[70:71], v[230:231], v[94:95], v[70:71] op_sel_hi:[1,0,1]
	v_pk_fma_f32 v[72:73], v[232:233], v[94:95], v[72:73] op_sel_hi:[1,0,1]
	v_pk_fma_f32 v[74:75], v[234:235], v[94:95], v[74:75] op_sel_hi:[1,0,1]
	v_pk_fma_f32 v[76:77], v[236:237], v[94:95], v[76:77] op_sel_hi:[1,0,1]
	v_pk_fma_f32 v[78:79], v[238:239], v[94:95], v[78:79] op_sel_hi:[1,0,1]
	global_load_dword v94, v240, s[100:101] nt
	s_add_u32 s100, s100, 0x3000
	s_addc_u32 s101, s101, 0
	ds_read_b128 v[208:211], v9 offset:2688
	ds_read_b128 v[212:215], v9 offset:2704
	ds_read_b128 v[216:219], v9 offset:2720
	ds_read_b128 v[220:223], v9 offset:2736
	s_waitcnt vmcnt(31) lgkmcnt(8)
	v_pk_fma_f32 v[64:65], v[176:177], v[96:97], v[64:65] op_sel_hi:[1,0,1]
	v_pk_fma_f32 v[66:67], v[178:179], v[96:97], v[66:67] op_sel_hi:[1,0,1]
	v_pk_fma_f32 v[68:69], v[180:181], v[96:97], v[68:69] op_sel_hi:[1,0,1]
	v_pk_fma_f32 v[70:71], v[182:183], v[96:97], v[70:71] op_sel_hi:[1,0,1]
	v_pk_fma_f32 v[72:73], v[184:185], v[96:97], v[72:73] op_sel_hi:[1,0,1]
	v_pk_fma_f32 v[74:75], v[186:187], v[96:97], v[74:75] op_sel_hi:[1,0,1]
	v_pk_fma_f32 v[76:77], v[188:189], v[96:97], v[76:77] op_sel_hi:[1,0,1]
	v_pk_fma_f32 v[78:79], v[190:191], v[96:97], v[78:79] op_sel_hi:[1,0,1]
	global_load_dword v96, v240, s[100:101] nt
	s_add_u32 s100, s100, 0x3000
	s_addc_u32 s101, s101, 0
	ds_read_b128 v[224:227], v9 offset:2752
	ds_read_b128 v[228:231], v9 offset:2768
	ds_read_b128 v[232:235], v9 offset:2784
	ds_read_b128 v[236:239], v9 offset:2800
	s_waitcnt vmcnt(31) lgkmcnt(8)
	v_pk_fma_f32 v[64:65], v[192:193], v[98:99], v[64:65] op_sel_hi:[1,0,1]
	v_pk_fma_f32 v[66:67], v[194:195], v[98:99], v[66:67] op_sel_hi:[1,0,1]
	v_pk_fma_f32 v[68:69], v[196:197], v[98:99], v[68:69] op_sel_hi:[1,0,1]
	v_pk_fma_f32 v[70:71], v[198:199], v[98:99], v[70:71] op_sel_hi:[1,0,1]
	v_pk_fma_f32 v[72:73], v[200:201], v[98:99], v[72:73] op_sel_hi:[1,0,1]
	v_pk_fma_f32 v[74:75], v[202:203], v[98:99], v[74:75] op_sel_hi:[1,0,1]
	v_pk_fma_f32 v[76:77], v[204:205], v[98:99], v[76:77] op_sel_hi:[1,0,1]
	v_pk_fma_f32 v[78:79], v[206:207], v[98:99], v[78:79] op_sel_hi:[1,0,1]
	global_load_dword v98, v240, s[100:101] nt
	s_add_u32 s100, s100, 0x3000
	s_addc_u32 s101, s101, 0
	ds_read_b128 v[176:179], v9 offset:2816
	ds_read_b128 v[180:183], v9 offset:2832
	ds_read_b128 v[184:187], v9 offset:2848
	ds_read_b128 v[188:191], v9 offset:2864
	s_waitcnt vmcnt(31) lgkmcnt(8)
	v_pk_fma_f32 v[64:65], v[208:209], v[100:101], v[64:65] op_sel_hi:[1,0,1]
	v_pk_fma_f32 v[66:67], v[210:211], v[100:101], v[66:67] op_sel_hi:[1,0,1]
	v_pk_fma_f32 v[68:69], v[212:213], v[100:101], v[68:69] op_sel_hi:[1,0,1]
	v_pk_fma_f32 v[70:71], v[214:215], v[100:101], v[70:71] op_sel_hi:[1,0,1]
	v_pk_fma_f32 v[72:73], v[216:217], v[100:101], v[72:73] op_sel_hi:[1,0,1]
	v_pk_fma_f32 v[74:75], v[218:219], v[100:101], v[74:75] op_sel_hi:[1,0,1]
	v_pk_fma_f32 v[76:77], v[220:221], v[100:101], v[76:77] op_sel_hi:[1,0,1]
	v_pk_fma_f32 v[78:79], v[222:223], v[100:101], v[78:79] op_sel_hi:[1,0,1]
	global_load_dword v100, v240, s[100:101] nt
	s_add_u32 s100, s100, 0x3000
	s_addc_u32 s101, s101, 0
	ds_read_b128 v[192:195], v9 offset:2880
	ds_read_b128 v[196:199], v9 offset:2896
	ds_read_b128 v[200:203], v9 offset:2912
	ds_read_b128 v[204:207], v9 offset:2928
	s_waitcnt vmcnt(31) lgkmcnt(8)
	v_pk_fma_f32 v[64:65], v[224:225], v[102:103], v[64:65] op_sel_hi:[1,0,1]
	v_pk_fma_f32 v[66:67], v[226:227], v[102:103], v[66:67] op_sel_hi:[1,0,1]
	v_pk_fma_f32 v[68:69], v[228:229], v[102:103], v[68:69] op_sel_hi:[1,0,1]
	v_pk_fma_f32 v[70:71], v[230:231], v[102:103], v[70:71] op_sel_hi:[1,0,1]
	v_pk_fma_f32 v[72:73], v[232:233], v[102:103], v[72:73] op_sel_hi:[1,0,1]
	v_pk_fma_f32 v[74:75], v[234:235], v[102:103], v[74:75] op_sel_hi:[1,0,1]
	v_pk_fma_f32 v[76:77], v[236:237], v[102:103], v[76:77] op_sel_hi:[1,0,1]
	v_pk_fma_f32 v[78:79], v[238:239], v[102:103], v[78:79] op_sel_hi:[1,0,1]
	global_load_dword v102, v240, s[100:101] nt
	s_add_u32 s100, s100, 0x3000
	s_addc_u32 s101, s101, 0
	ds_read_b128 v[208:211], v9 offset:2944
	ds_read_b128 v[212:215], v9 offset:2960
	ds_read_b128 v[216:219], v9 offset:2976
	ds_read_b128 v[220:223], v9 offset:2992
	s_waitcnt vmcnt(31) lgkmcnt(8)
; #define LAS __attribute__((address_space(3)))
; __device__ __forceinline__ void ada_block(const Params& p, LAS unsigned char* lds, int blk, int tid) {
;     ...
;     for (int kk = 0; kk < 128; ++kk) {
;         const float wv = __builtin_nontemporal_load(wp + (size_t)kk * 3072);
;         const LAS f32x4* cp = (const LAS f32x4*)(cs + (w * 128 + kk) * 16);
;         a0 += cp[0] * wv; a1 += cp[1] * wv; a2 += cp[2] * wv; a3 += cp[3] * wv;
;     }
	v_pk_fma_f32 v[64:65], v[176:177], v[104:105], v[64:65] op_sel_hi:[1,0,1]
	v_pk_fma_f32 v[66:67], v[178:179], v[104:105], v[66:67] op_sel_hi:[1,0,1]
	v_pk_fma_f32 v[68:69], v[180:181], v[104:105], v[68:69] op_sel_hi:[1,0,1]
	v_pk_fma_f32 v[70:71], v[182:183], v[104:105], v[70:71] op_sel_hi:[1,0,1]
	v_pk_fma_f32 v[72:73], v[184:185], v[104:105], v[72:73] op_sel_hi:[1,0,1]
	v_pk_fma_f32 v[74:75], v[186:187], v[104:105], v[74:75] op_sel_hi:[1,0,1]
	v_pk_fma_f32 v[76:77], v[188:189], v[104:105], v[76:77] op_sel_hi:[1,0,1]
	v_pk_fma_f32 v[78:79], v[190:191], v[104:105], v[78:79] op_sel_hi:[1,0,1]
	global_load_dword v104, v240, s[100:101] nt
	s_add_u32 s100, s100, 0x3000
	s_addc_u32 s101, s101, 0
	ds_read_b128 v[224:227], v9 offset:3008
	ds_read_b128 v[228:231], v9 offset:3024
	ds_read_b128 v[232:235], v9 offset:3040
	ds_read_b128 v[236:239], v9 offset:3056
	s_waitcnt vmcnt(31) lgkmcnt(8)
	v_pk_fma_f32 v[64:65], v[192:193], v[106:107], v[64:65] op_sel_hi:[1,0,1]
	v_pk_fma_f32 v[66:67], v[194:195], v[106:107], v[66:67] op_sel_hi:[1,0,1]
	v_pk_fma_f32 v[68:69], v[196:197], v[106:107], v[68:69] op_sel_hi:[1,0,1]
	v_pk_fma_f32 v[70:71], v[198:199], v[106:107], v[70:71] op_sel_hi:[1,0,1]
	v_pk_fma_f32 v[72:73], v[200:201], v[106:107], v[72:73] op_sel_hi:[1,0,1]
	v_pk_fma_f32 v[74:75], v[202:203], v[106:107], v[74:75] op_sel_hi:[1,0,1]
	v_pk_fma_f32 v[76:77], v[204:205], v[106:107], v[76:77] op_sel_hi:[1,0,1]
	v_pk_fma_f32 v[78:79], v[206:207], v[106:107], v[78:79] op_sel_hi:[1,0,1]
	global_load_dword v106, v240, s[100:101] nt
	s_add_u32 s100, s100, 0x3000
	s_addc_u32 s101, s101, 0
	ds_read_b128 v[176:179], v9 offset:3072
	ds_read_b128 v[180:183], v9 offset:3088
	ds_read_b128 v[184:187], v9 offset:3104
	ds_read_b128 v[188:191], v9 offset:3120
	s_waitcnt vmcnt(31) lgkmcnt(8)
	v_pk_fma_f32 v[64:65], v[208:209], v[108:109], v[64:65] op_sel_hi:[1,0,1]
	v_pk_fma_f32 v[66:67], v[210:211], v[108:109], v[66:67] op_sel_hi:[1,0,1]
	v_pk_fma_f32 v[68:69], v[212:213], v[108:109], v[68:69] op_sel_hi:[1,0,1]
	v_pk_fma_f32 v[70:71], v[214:215], v[108:109], v[70:71] op_sel_hi:[1,0,1]
	v_pk_fma_f32 v[72:73], v[216:217], v[108:109], v[72:73] op_sel_hi:[1,0,1]
	v_pk_fma_f32 v[74:75], v[218:219], v[108:109], v[74:75] op_sel_hi:[1,0,1]
	v_pk_fma_f32 v[76:77], v[220:221], v[108:109], v[76:77] op_sel_hi:[1,0,1]
	v_pk_fma_f32 v[78:79], v[222:223], v[108:109], v[78:79] op_sel_hi:[1,0,1]
	global_load_dword v108, v240, s[100:101] nt
	s_add_u32 s100, s100, 0x3000
	s_addc_u32 s101, s101, 0
	ds_read_b128 v[192:195], v9 offset:3136
	ds_read_b128 v[196:199], v9 offset:3152
	ds_read_b128 v[200:203], v9 offset:3168
	ds_read_b128 v[204:207], v9 offset:3184
	s_waitcnt vmcnt(31) lgkmcnt(8)
	v_pk_fma_f32 v[64:65], v[224:225], v[110:111], v[64:65] op_sel_hi:[1,0,1]
	v_pk_fma_f32 v[66:67], v[226:227], v[110:111], v[66:67] op_sel_hi:[1,0,1]
	v_pk_fma_f32 v[68:69], v[228:229], v[110:111], v[68:69] op_sel_hi:[1,0,1]
	v_pk_fma_f32 v[70:71], v[230:231], v[110:111], v[70:71] op_sel_hi:[1,0,1]
	v_pk_fma_f32 v[72:73], v[232:233], v[110:111], v[72:73] op_sel_hi:[1,0,1]
	v_pk_fma_f32 v[74:75], v[234:235], v[110:111], v[74:75] op_sel_hi:[1,0,1]
	v_pk_fma_f32 v[76:77], v[236:237], v[110:111], v[76:77] op_sel_hi:[1,0,1]
	v_pk_fma_f32 v[78:79], v[238:239], v[110:111], v[78:79] op_sel_hi:[1,0,1]
	global_load_dword v110, v240, s[100:101] nt
	s_add_u32 s100, s100, 0x3000
	s_addc_u32 s101, s101, 0
	ds_read_b128 v[208:211], v9 offset:3200
	ds_read_b128 v[212:215], v9 offset:3216
	ds_read_b128 v[216:219], v9 offset:3232
	ds_read_b128 v[220:223], v9 offset:3248
	s_waitcnt vmcnt(31) lgkmcnt(8)
	v_pk_fma_f32 v[64:65], v[176:177], v[112:113], v[64:65] op_sel_hi:[1,0,1]
	v_pk_fma_f32 v[66:67], v[178:179], v[112:113], v[66:67] op_sel_hi:[1,0,1]
	v_pk_fma_f32 v[68:69], v[180:181], v[112:113], v[68:69] op_sel_hi:[1,0,1]
	v_pk_fma_f32 v[70:71], v[182:183], v[112:113], v[70:71] op_sel_hi:[1,0,1]
	v_pk_fma_f32 v[72:73], v[184:185], v[112:113], v[72:73] op_sel_hi:[1,0,1]
	v_pk_fma_f32 v[74:75], v[186:187], v[112:113], v[74:75] op_sel_hi:[1,0,1]
	v_pk_fma_f32 v[76:77], v[188:189], v[112:113], v[76:77] op_sel_hi:[1,0,1]
	v_pk_fma_f32 v[78:79], v[190:191], v[112:113], v[78:79] op_sel_hi:[1,0,1]
	global_load_dword v112, v240, s[100:101] nt
	s_add_u32 s100, s100, 0x3000
	s_addc_u32 s101, s101, 0
	ds_read_b128 v[224:227], v9 offset:3264
	ds_read_b128 v[228:231], v9 offset:3280
	ds_read_b128 v[232:235], v9 offset:3296
	ds_read_b128 v[236:239], v9 offset:3312
	s_waitcnt vmcnt(31) lgkmcnt(8)
	v_pk_fma_f32 v[64:65], v[192:193], v[114:115], v[64:65] op_sel_hi:[1,0,1]
	v_pk_fma_f32 v[66:67], v[194:195], v[114:115], v[66:67] op_sel_hi:[1,0,1]
	v_pk_fma_f32 v[68:69], v[196:197], v[114:115], v[68:69] op_sel_hi:[1,0,1]
	v_pk_fma_f32 v[70:71], v[198:199], v[114:115], v[70:71] op_sel_hi:[1,0,1]
	v_pk_fma_f32 v[72:73], v[200:201], v[114:115], v[72:73] op_sel_hi:[1,0,1]
	v_pk_fma_f32 v[74:75], v[202:203], v[114:115], v[74:75] op_sel_hi:[1,0,1]
	v_pk_fma_f32 v[76:77], v[204:205], v[114:115], v[76:77] op_sel_hi:[1,0,1]
	v_pk_fma_f32 v[78:79], v[206:207], v[114:115], v[78:79] op_sel_hi:[1,0,1]
	global_load_dword v114, v240, s[100:101] nt
	s_add_u32 s100, s100, 0x3000
	s_addc_u32 s101, s101, 0
	ds_read_b128 v[176:179], v9 offset:3328
	ds_read_b128 v[180:183], v9 offset:3344
	ds_read_b128 v[184:187], v9 offset:3360
	ds_read_b128 v[188:191], v9 offset:3376
	s_waitcnt vmcnt(31) lgkmcnt(8)
; #define LAS __attribute__((address_space(3)))
; __device__ __forceinline__ void ada_block(const Params& p, LAS unsigned char* lds, int blk, int tid) {
;     ...
;     for (int kk = 0; kk < 128; ++kk) {
;         const float wv = __builtin_nontemporal_load(wp + (size_t)kk * 3072);
;         const LAS f32x4* cp = (const LAS f32x4*)(cs + (w * 128 + kk) * 16);
;         a0 += cp[0] * wv; a1 += cp[1] * wv; a2 += cp[2] * wv; a3 += cp[3] * wv;
;     }
	v_pk_fma_f32 v[64:65], v[208:209], v[116:117], v[64:65] op_sel_hi:[1,0,1]
	v_pk_fma_f32 v[66:67], v[210:211], v[116:117], v[66:67] op_sel_hi:[1,0,1]
	v_pk_fma_f32 v[68:69], v[212:213], v[116:117], v[68:69] op_sel_hi:[1,0,1]
	v_pk_fma_f32 v[70:71], v[214:215], v[116:117], v[70:71] op_sel_hi:[1,0,1]
	v_pk_fma_f32 v[72:73], v[216:217], v[116:117], v[72:73] op_sel_hi:[1,0,1]
	v_pk_fma_f32 v[74:75], v[218:219], v[116:117], v[74:75] op_sel_hi:[1,0,1]
	v_pk_fma_f32 v[76:77], v[220:221], v[116:117], v[76:77] op_sel_hi:[1,0,1]
	v_pk_fma_f32 v[78:79], v[222:223], v[116:117], v[78:79] op_sel_hi:[1,0,1]
	global_load_dword v116, v240, s[100:101] nt
	s_add_u32 s100, s100, 0x3000
	s_addc_u32 s101, s101, 0
	ds_read_b128 v[192:195], v9 offset:3392
	ds_read_b128 v[196:199], v9 offset:3408
	ds_read_b128 v[200:203], v9 offset:3424
	ds_read_b128 v[204:207], v9 offset:3440
	s_waitcnt vmcnt(31) lgkmcnt(8)
	v_pk_fma_f32 v[64:65], v[224:225], v[118:119], v[64:65] op_sel_hi:[1,0,1]
	v_pk_fma_f32 v[66:67], v[226:227], v[118:119], v[66:67] op_sel_hi:[1,0,1]
	v_pk_fma_f32 v[68:69], v[228:229], v[118:119], v[68:69] op_sel_hi:[1,0,1]
	v_pk_fma_f32 v[70:71], v[230:231], v[118:119], v[70:71] op_sel_hi:[1,0,1]
	v_pk_fma_f32 v[72:73], v[232:233], v[118:119], v[72:73] op_sel_hi:[1,0,1]
	v_pk_fma_f32 v[74:75], v[234:235], v[118:119], v[74:75] op_sel_hi:[1,0,1]
	v_pk_fma_f32 v[76:77], v[236:237], v[118:119], v[76:77] op_sel_hi:[1,0,1]
	v_pk_fma_f32 v[78:79], v[238:239], v[118:119], v[78:79] op_sel_hi:[1,0,1]
	global_load_dword v118, v240, s[100:101] nt
	s_add_u32 s100, s100, 0x3000
	s_addc_u32 s101, s101, 0
	ds_read_b128 v[208:211], v9 offset:3456
	ds_read_b128 v[212:215], v9 offset:3472
	ds_read_b128 v[216:219], v9 offset:3488
	ds_read_b128 v[220:223], v9 offset:3504
	s_waitcnt vmcnt(31) lgkmcnt(8)
	v_pk_fma_f32 v[64:65], v[176:177], v[120:121], v[64:65] op_sel_hi:[1,0,1]
	v_pk_fma_f32 v[66:67], v[178:179], v[120:121], v[66:67] op_sel_hi:[1,0,1]
	v_pk_fma_f32 v[68:69], v[180:181], v[120:121], v[68:69] op_sel_hi:[1,0,1]
	v_pk_fma_f32 v[70:71], v[182:183], v[120:121], v[70:71] op_sel_hi:[1,0,1]
	v_pk_fma_f32 v[72:73], v[184:185], v[120:121], v[72:73] op_sel_hi:[1,0,1]
	v_pk_fma_f32 v[74:75], v[186:187], v[120:121], v[74:75] op_sel_hi:[1,0,1]
	v_pk_fma_f32 v[76:77], v[188:189], v[120:121], v[76:77] op_sel_hi:[1,0,1]
	v_pk_fma_f32 v[78:79], v[190:191], v[120:121], v[78:79] op_sel_hi:[1,0,1]
	global_load_dword v120, v240, s[100:101] nt
	s_add_u32 s100, s100, 0x3000
	s_addc_u32 s101, s101, 0
	ds_read_b128 v[224:227], v9 offset:3520
	ds_read_b128 v[228:231], v9 offset:3536
	ds_read_b128 v[232:235], v9 offset:3552
	ds_read_b128 v[236:239], v9 offset:3568
	s_waitcnt vmcnt(31) lgkmcnt(8)
	v_pk_fma_f32 v[64:65], v[192:193], v[122:123], v[64:65] op_sel_hi:[1,0,1]
	v_pk_fma_f32 v[66:67], v[194:195], v[122:123], v[66:67] op_sel_hi:[1,0,1]
	v_pk_fma_f32 v[68:69], v[196:197], v[122:123], v[68:69] op_sel_hi:[1,0,1]
	v_pk_fma_f32 v[70:71], v[198:199], v[122:123], v[70:71] op_sel_hi:[1,0,1]
	v_pk_fma_f32 v[72:73], v[200:201], v[122:123], v[72:73] op_sel_hi:[1,0,1]
	v_pk_fma_f32 v[74:75], v[202:203], v[122:123], v[74:75] op_sel_hi:[1,0,1]
	v_pk_fma_f32 v[76:77], v[204:205], v[122:123], v[76:77] op_sel_hi:[1,0,1]
	v_pk_fma_f32 v[78:79], v[206:207], v[122:123], v[78:79] op_sel_hi:[1,0,1]
	global_load_dword v122, v240, s[100:101] nt
	s_add_u32 s100, s100, 0x3000
	s_addc_u32 s101, s101, 0
	ds_read_b128 v[176:179], v9 offset:3584
	ds_read_b128 v[180:183], v9 offset:3600
	ds_read_b128 v[184:187], v9 offset:3616
	ds_read_b128 v[188:191], v9 offset:3632
	s_waitcnt vmcnt(31) lgkmcnt(8)
	v_pk_fma_f32 v[64:65], v[208:209], v[124:125], v[64:65] op_sel_hi:[1,0,1]
	v_pk_fma_f32 v[66:67], v[210:211], v[124:125], v[66:67] op_sel_hi:[1,0,1]
	v_pk_fma_f32 v[68:69], v[212:213], v[124:125], v[68:69] op_sel_hi:[1,0,1]
	v_pk_fma_f32 v[70:71], v[214:215], v[124:125], v[70:71] op_sel_hi:[1,0,1]
	v_pk_fma_f32 v[72:73], v[216:217], v[124:125], v[72:73] op_sel_hi:[1,0,1]
	v_pk_fma_f32 v[74:75], v[218:219], v[124:125], v[74:75] op_sel_hi:[1,0,1]
	v_pk_fma_f32 v[76:77], v[220:221], v[124:125], v[76:77] op_sel_hi:[1,0,1]
	v_pk_fma_f32 v[78:79], v[222:223], v[124:125], v[78:79] op_sel_hi:[1,0,1]
	global_load_dword v124, v240, s[100:101] nt
	s_add_u32 s100, s100, 0x3000
	s_addc_u32 s101, s101, 0
	ds_read_b128 v[192:195], v9 offset:3648
	ds_read_b128 v[196:199], v9 offset:3664
	ds_read_b128 v[200:203], v9 offset:3680
	ds_read_b128 v[204:207], v9 offset:3696
	s_waitcnt vmcnt(31) lgkmcnt(8)
	v_pk_fma_f32 v[64:65], v[224:225], v[126:127], v[64:65] op_sel_hi:[1,0,1]
	v_pk_fma_f32 v[66:67], v[226:227], v[126:127], v[66:67] op_sel_hi:[1,0,1]
	v_pk_fma_f32 v[68:69], v[228:229], v[126:127], v[68:69] op_sel_hi:[1,0,1]
	v_pk_fma_f32 v[70:71], v[230:231], v[126:127], v[70:71] op_sel_hi:[1,0,1]
	v_pk_fma_f32 v[72:73], v[232:233], v[126:127], v[72:73] op_sel_hi:[1,0,1]
	v_pk_fma_f32 v[74:75], v[234:235], v[126:127], v[74:75] op_sel_hi:[1,0,1]
	v_pk_fma_f32 v[76:77], v[236:237], v[126:127], v[76:77] op_sel_hi:[1,0,1]
	v_pk_fma_f32 v[78:79], v[238:239], v[126:127], v[78:79] op_sel_hi:[1,0,1]
	global_load_dword v126, v240, s[100:101] nt
	s_add_u32 s100, s100, 0x3000
	s_addc_u32 s101, s101, 0
	ds_read_b128 v[208:211], v9 offset:3712
	ds_read_b128 v[212:215], v9 offset:3728
	ds_read_b128 v[216:219], v9 offset:3744
	ds_read_b128 v[220:223], v9 offset:3760
	s_waitcnt vmcnt(31) lgkmcnt(8)
; #define LAS __attribute__((address_space(3)))
; __device__ __forceinline__ void ada_block(const Params& p, LAS unsigned char* lds, int blk, int tid) {
;     ...
;     for (int kk = 0; kk < 128; ++kk) {
;         const float wv = __builtin_nontemporal_load(wp + (size_t)kk * 3072);
;         const LAS f32x4* cp = (const LAS f32x4*)(cs + (w * 128 + kk) * 16);
;         a0 += cp[0] * wv; a1 += cp[1] * wv; a2 += cp[2] * wv; a3 += cp[3] * wv;
;     }
	v_pk_fma_f32 v[64:65], v[176:177], v[128:129], v[64:65] op_sel_hi:[1,0,1]
	v_pk_fma_f32 v[66:67], v[178:179], v[128:129], v[66:67] op_sel_hi:[1,0,1]
	v_pk_fma_f32 v[68:69], v[180:181], v[128:129], v[68:69] op_sel_hi:[1,0,1]
	v_pk_fma_f32 v[70:71], v[182:183], v[128:129], v[70:71] op_sel_hi:[1,0,1]
	v_pk_fma_f32 v[72:73], v[184:185], v[128:129], v[72:73] op_sel_hi:[1,0,1]
	v_pk_fma_f32 v[74:75], v[186:187], v[128:129], v[74:75] op_sel_hi:[1,0,1]
	v_pk_fma_f32 v[76:77], v[188:189], v[128:129], v[76:77] op_sel_hi:[1,0,1]
	v_pk_fma_f32 v[78:79], v[190:191], v[128:129], v[78:79] op_sel_hi:[1,0,1]
	global_load_dword v128, v240, s[100:101] nt
	s_add_u32 s100, s100, 0x3000
	s_addc_u32 s101, s101, 0
	ds_read_b128 v[224:227], v9 offset:3776
	ds_read_b128 v[228:231], v9 offset:3792
	ds_read_b128 v[232:235], v9 offset:3808
	ds_read_b128 v[236:239], v9 offset:3824
	s_waitcnt vmcnt(31) lgkmcnt(8)
	v_pk_fma_f32 v[64:65], v[192:193], v[130:131], v[64:65] op_sel_hi:[1,0,1]
	v_pk_fma_f32 v[66:67], v[194:195], v[130:131], v[66:67] op_sel_hi:[1,0,1]
	v_pk_fma_f32 v[68:69], v[196:197], v[130:131], v[68:69] op_sel_hi:[1,0,1]
	v_pk_fma_f32 v[70:71], v[198:199], v[130:131], v[70:71] op_sel_hi:[1,0,1]
	v_pk_fma_f32 v[72:73], v[200:201], v[130:131], v[72:73] op_sel_hi:[1,0,1]
	v_pk_fma_f32 v[74:75], v[202:203], v[130:131], v[74:75] op_sel_hi:[1,0,1]
	v_pk_fma_f32 v[76:77], v[204:205], v[130:131], v[76:77] op_sel_hi:[1,0,1]
	v_pk_fma_f32 v[78:79], v[206:207], v[130:131], v[78:79] op_sel_hi:[1,0,1]
	global_load_dword v130, v240, s[100:101] nt
	s_add_u32 s100, s100, 0x3000
	s_addc_u32 s101, s101, 0
	ds_read_b128 v[176:179], v9 offset:3840
	ds_read_b128 v[180:183], v9 offset:3856
	ds_read_b128 v[184:187], v9 offset:3872
	ds_read_b128 v[188:191], v9 offset:3888
	s_waitcnt vmcnt(31) lgkmcnt(8)
	v_pk_fma_f32 v[64:65], v[208:209], v[132:133], v[64:65] op_sel_hi:[1,0,1]
	v_pk_fma_f32 v[66:67], v[210:211], v[132:133], v[66:67] op_sel_hi:[1,0,1]
	v_pk_fma_f32 v[68:69], v[212:213], v[132:133], v[68:69] op_sel_hi:[1,0,1]
	v_pk_fma_f32 v[70:71], v[214:215], v[132:133], v[70:71] op_sel_hi:[1,0,1]
	v_pk_fma_f32 v[72:73], v[216:217], v[132:133], v[72:73] op_sel_hi:[1,0,1]
	v_pk_fma_f32 v[74:75], v[218:219], v[132:133], v[74:75] op_sel_hi:[1,0,1]
	v_pk_fma_f32 v[76:77], v[220:221], v[132:133], v[76:77] op_sel_hi:[1,0,1]
	v_pk_fma_f32 v[78:79], v[222:223], v[132:133], v[78:79] op_sel_hi:[1,0,1]
	global_load_dword v132, v240, s[100:101] nt
	s_add_u32 s100, s100, 0x3000
	s_addc_u32 s101, s101, 0
	ds_read_b128 v[192:195], v9 offset:3904
	ds_read_b128 v[196:199], v9 offset:3920
	ds_read_b128 v[200:203], v9 offset:3936
	ds_read_b128 v[204:207], v9 offset:3952
	s_waitcnt vmcnt(31) lgkmcnt(8)
	v_pk_fma_f32 v[64:65], v[224:225], v[134:135], v[64:65] op_sel_hi:[1,0,1]
	v_pk_fma_f32 v[66:67], v[226:227], v[134:135], v[66:67] op_sel_hi:[1,0,1]
	v_pk_fma_f32 v[68:69], v[228:229], v[134:135], v[68:69] op_sel_hi:[1,0,1]
	v_pk_fma_f32 v[70:71], v[230:231], v[134:135], v[70:71] op_sel_hi:[1,0,1]
	v_pk_fma_f32 v[72:73], v[232:233], v[134:135], v[72:73] op_sel_hi:[1,0,1]
	v_pk_fma_f32 v[74:75], v[234:235], v[134:135], v[74:75] op_sel_hi:[1,0,1]
	v_pk_fma_f32 v[76:77], v[236:237], v[134:135], v[76:77] op_sel_hi:[1,0,1]
	v_pk_fma_f32 v[78:79], v[238:239], v[134:135], v[78:79] op_sel_hi:[1,0,1]
	global_load_dword v134, v240, s[100:101] nt
	s_add_u32 s100, s100, 0x3000
	s_addc_u32 s101, s101, 0
	ds_read_b128 v[208:211], v9 offset:3968
	ds_read_b128 v[212:215], v9 offset:3984
	ds_read_b128 v[216:219], v9 offset:4000
	ds_read_b128 v[220:223], v9 offset:4016
	s_waitcnt vmcnt(31) lgkmcnt(8)
	v_pk_fma_f32 v[64:65], v[176:177], v[136:137], v[64:65] op_sel_hi:[1,0,1]
	v_pk_fma_f32 v[66:67], v[178:179], v[136:137], v[66:67] op_sel_hi:[1,0,1]
	v_pk_fma_f32 v[68:69], v[180:181], v[136:137], v[68:69] op_sel_hi:[1,0,1]
	v_pk_fma_f32 v[70:71], v[182:183], v[136:137], v[70:71] op_sel_hi:[1,0,1]
	v_pk_fma_f32 v[72:73], v[184:185], v[136:137], v[72:73] op_sel_hi:[1,0,1]
	v_pk_fma_f32 v[74:75], v[186:187], v[136:137], v[74:75] op_sel_hi:[1,0,1]
	v_pk_fma_f32 v[76:77], v[188:189], v[136:137], v[76:77] op_sel_hi:[1,0,1]
	v_pk_fma_f32 v[78:79], v[190:191], v[136:137], v[78:79] op_sel_hi:[1,0,1]
	global_load_dword v136, v240, s[100:101] nt
	s_add_u32 s100, s100, 0x3000
	s_addc_u32 s101, s101, 0
	ds_read_b128 v[224:227], v9 offset:4032
	ds_read_b128 v[228:231], v9 offset:4048
	ds_read_b128 v[232:235], v9 offset:4064
	ds_read_b128 v[236:239], v9 offset:4080
	s_waitcnt vmcnt(31) lgkmcnt(8)
	v_pk_fma_f32 v[64:65], v[192:193], v[138:139], v[64:65] op_sel_hi:[1,0,1]
	v_pk_fma_f32 v[66:67], v[194:195], v[138:139], v[66:67] op_sel_hi:[1,0,1]
	v_pk_fma_f32 v[68:69], v[196:197], v[138:139], v[68:69] op_sel_hi:[1,0,1]
	v_pk_fma_f32 v[70:71], v[198:199], v[138:139], v[70:71] op_sel_hi:[1,0,1]
	v_pk_fma_f32 v[72:73], v[200:201], v[138:139], v[72:73] op_sel_hi:[1,0,1]
	v_pk_fma_f32 v[74:75], v[202:203], v[138:139], v[74:75] op_sel_hi:[1,0,1]
	v_pk_fma_f32 v[76:77], v[204:205], v[138:139], v[76:77] op_sel_hi:[1,0,1]
	v_pk_fma_f32 v[78:79], v[206:207], v[138:139], v[78:79] op_sel_hi:[1,0,1]
	global_load_dword v138, v240, s[100:101] nt
	s_add_u32 s100, s100, 0x3000
	s_addc_u32 s101, s101, 0
	ds_read_b128 v[176:179], v9 offset:4096
	ds_read_b128 v[180:183], v9 offset:4112
	ds_read_b128 v[184:187], v9 offset:4128
	ds_read_b128 v[188:191], v9 offset:4144
	s_waitcnt vmcnt(31) lgkmcnt(8)
; #define LAS __attribute__((address_space(3)))
; __device__ __forceinline__ void ada_block(const Params& p, LAS unsigned char* lds, int blk, int tid) {
;     ...
;     for (int kk = 0; kk < 128; ++kk) {
;         const float wv = __builtin_nontemporal_load(wp + (size_t)kk * 3072);
;         const LAS f32x4* cp = (const LAS f32x4*)(cs + (w * 128 + kk) * 16);
;         a0 += cp[0] * wv; a1 += cp[1] * wv; a2 += cp[2] * wv; a3 += cp[3] * wv;
;     }
	v_pk_fma_f32 v[64:65], v[208:209], v[140:141], v[64:65] op_sel_hi:[1,0,1]
	v_pk_fma_f32 v[66:67], v[210:211], v[140:141], v[66:67] op_sel_hi:[1,0,1]
	v_pk_fma_f32 v[68:69], v[212:213], v[140:141], v[68:69] op_sel_hi:[1,0,1]
	v_pk_fma_f32 v[70:71], v[214:215], v[140:141], v[70:71] op_sel_hi:[1,0,1]
	v_pk_fma_f32 v[72:73], v[216:217], v[140:141], v[72:73] op_sel_hi:[1,0,1]
	v_pk_fma_f32 v[74:75], v[218:219], v[140:141], v[74:75] op_sel_hi:[1,0,1]
	v_pk_fma_f32 v[76:77], v[220:221], v[140:141], v[76:77] op_sel_hi:[1,0,1]
	v_pk_fma_f32 v[78:79], v[222:223], v[140:141], v[78:79] op_sel_hi:[1,0,1]
	global_load_dword v140, v240, s[100:101] nt
	s_add_u32 s100, s100, 0x3000
	s_addc_u32 s101, s101, 0
	ds_read_b128 v[192:195], v9 offset:4160
	ds_read_b128 v[196:199], v9 offset:4176
	ds_read_b128 v[200:203], v9 offset:4192
	ds_read_b128 v[204:207], v9 offset:4208
	s_waitcnt vmcnt(31) lgkmcnt(8)
	v_pk_fma_f32 v[64:65], v[224:225], v[142:143], v[64:65] op_sel_hi:[1,0,1]
	v_pk_fma_f32 v[66:67], v[226:227], v[142:143], v[66:67] op_sel_hi:[1,0,1]
	v_pk_fma_f32 v[68:69], v[228:229], v[142:143], v[68:69] op_sel_hi:[1,0,1]
	v_pk_fma_f32 v[70:71], v[230:231], v[142:143], v[70:71] op_sel_hi:[1,0,1]
	v_pk_fma_f32 v[72:73], v[232:233], v[142:143], v[72:73] op_sel_hi:[1,0,1]
	v_pk_fma_f32 v[74:75], v[234:235], v[142:143], v[74:75] op_sel_hi:[1,0,1]
	v_pk_fma_f32 v[76:77], v[236:237], v[142:143], v[76:77] op_sel_hi:[1,0,1]
	v_pk_fma_f32 v[78:79], v[238:239], v[142:143], v[78:79] op_sel_hi:[1,0,1]
	global_load_dword v142, v240, s[100:101] nt
	s_add_u32 s100, s100, 0x3000
	s_addc_u32 s101, s101, 0
	ds_read_b128 v[208:211], v9 offset:4224
	ds_read_b128 v[212:215], v9 offset:4240
	ds_read_b128 v[216:219], v9 offset:4256
	ds_read_b128 v[220:223], v9 offset:4272
	s_waitcnt vmcnt(31) lgkmcnt(8)
	v_pk_fma_f32 v[64:65], v[176:177], v[80:81], v[64:65] op_sel_hi:[1,0,1]
	v_pk_fma_f32 v[66:67], v[178:179], v[80:81], v[66:67] op_sel_hi:[1,0,1]
	v_pk_fma_f32 v[68:69], v[180:181], v[80:81], v[68:69] op_sel_hi:[1,0,1]
	v_pk_fma_f32 v[70:71], v[182:183], v[80:81], v[70:71] op_sel_hi:[1,0,1]
	v_pk_fma_f32 v[72:73], v[184:185], v[80:81], v[72:73] op_sel_hi:[1,0,1]
	v_pk_fma_f32 v[74:75], v[186:187], v[80:81], v[74:75] op_sel_hi:[1,0,1]
	v_pk_fma_f32 v[76:77], v[188:189], v[80:81], v[76:77] op_sel_hi:[1,0,1]
	v_pk_fma_f32 v[78:79], v[190:191], v[80:81], v[78:79] op_sel_hi:[1,0,1]
	global_load_dword v80, v240, s[100:101] nt
	s_add_u32 s100, s100, 0x3000
	s_addc_u32 s101, s101, 0
	ds_read_b128 v[224:227], v9 offset:4288
	ds_read_b128 v[228:231], v9 offset:4304
	ds_read_b128 v[232:235], v9 offset:4320
	ds_read_b128 v[236:239], v9 offset:4336
	s_waitcnt vmcnt(31) lgkmcnt(8)
	v_pk_fma_f32 v[64:65], v[192:193], v[82:83], v[64:65] op_sel_hi:[1,0,1]
	v_pk_fma_f32 v[66:67], v[194:195], v[82:83], v[66:67] op_sel_hi:[1,0,1]
	v_pk_fma_f32 v[68:69], v[196:197], v[82:83], v[68:69] op_sel_hi:[1,0,1]
	v_pk_fma_f32 v[70:71], v[198:199], v[82:83], v[70:71] op_sel_hi:[1,0,1]
	v_pk_fma_f32 v[72:73], v[200:201], v[82:83], v[72:73] op_sel_hi:[1,0,1]
	v_pk_fma_f32 v[74:75], v[202:203], v[82:83], v[74:75] op_sel_hi:[1,0,1]
	v_pk_fma_f32 v[76:77], v[204:205], v[82:83], v[76:77] op_sel_hi:[1,0,1]
	v_pk_fma_f32 v[78:79], v[206:207], v[82:83], v[78:79] op_sel_hi:[1,0,1]
	global_load_dword v82, v240, s[100:101] nt
	s_add_u32 s100, s100, 0x3000
	s_addc_u32 s101, s101, 0
	ds_read_b128 v[176:179], v9 offset:4352
	ds_read_b128 v[180:183], v9 offset:4368
	ds_read_b128 v[184:187], v9 offset:4384
	ds_read_b128 v[188:191], v9 offset:4400
	s_waitcnt vmcnt(31) lgkmcnt(8)
	v_pk_fma_f32 v[64:65], v[208:209], v[84:85], v[64:65] op_sel_hi:[1,0,1]
	v_pk_fma_f32 v[66:67], v[210:211], v[84:85], v[66:67] op_sel_hi:[1,0,1]
	v_pk_fma_f32 v[68:69], v[212:213], v[84:85], v[68:69] op_sel_hi:[1,0,1]
	v_pk_fma_f32 v[70:71], v[214:215], v[84:85], v[70:71] op_sel_hi:[1,0,1]
	v_pk_fma_f32 v[72:73], v[216:217], v[84:85], v[72:73] op_sel_hi:[1,0,1]
	v_pk_fma_f32 v[74:75], v[218:219], v[84:85], v[74:75] op_sel_hi:[1,0,1]
	v_pk_fma_f32 v[76:77], v[220:221], v[84:85], v[76:77] op_sel_hi:[1,0,1]
	v_pk_fma_f32 v[78:79], v[222:223], v[84:85], v[78:79] op_sel_hi:[1,0,1]
	global_load_dword v84, v240, s[100:101] nt
	s_add_u32 s100, s100, 0x3000
	s_addc_u32 s101, s101, 0
	ds_read_b128 v[192:195], v9 offset:4416
	ds_read_b128 v[196:199], v9 offset:4432
	ds_read_b128 v[200:203], v9 offset:4448
	ds_read_b128 v[204:207], v9 offset:4464
	s_waitcnt vmcnt(31) lgkmcnt(8)
	v_pk_fma_f32 v[64:65], v[224:225], v[86:87], v[64:65] op_sel_hi:[1,0,1]
	v_pk_fma_f32 v[66:67], v[226:227], v[86:87], v[66:67] op_sel_hi:[1,0,1]
	v_pk_fma_f32 v[68:69], v[228:229], v[86:87], v[68:69] op_sel_hi:[1,0,1]
	v_pk_fma_f32 v[70:71], v[230:231], v[86:87], v[70:71] op_sel_hi:[1,0,1]
	v_pk_fma_f32 v[72:73], v[232:233], v[86:87], v[72:73] op_sel_hi:[1,0,1]
	v_pk_fma_f32 v[74:75], v[234:235], v[86:87], v[74:75] op_sel_hi:[1,0,1]
	v_pk_fma_f32 v[76:77], v[236:237], v[86:87], v[76:77] op_sel_hi:[1,0,1]
	v_pk_fma_f32 v[78:79], v[238:239], v[86:87], v[78:79] op_sel_hi:[1,0,1]
	global_load_dword v86, v240, s[100:101] nt
	s_add_u32 s100, s100, 0x3000
	s_addc_u32 s101, s101, 0
	ds_read_b128 v[208:211], v9 offset:4480
	ds_read_b128 v[212:215], v9 offset:4496
	ds_read_b128 v[216:219], v9 offset:4512
	ds_read_b128 v[220:223], v9 offset:4528
	s_waitcnt vmcnt(31) lgkmcnt(8)
; #define LAS __attribute__((address_space(3)))
; __device__ __forceinline__ void ada_block(const Params& p, LAS unsigned char* lds, int blk, int tid) {
;     ...
;     for (int kk = 0; kk < 128; ++kk) {
;         const float wv = __builtin_nontemporal_load(wp + (size_t)kk * 3072);
;         const LAS f32x4* cp = (const LAS f32x4*)(cs + (w * 128 + kk) * 16);
;         a0 += cp[0] * wv; a1 += cp[1] * wv; a2 += cp[2] * wv; a3 += cp[3] * wv;
;     }
	v_pk_fma_f32 v[64:65], v[176:177], v[88:89], v[64:65] op_sel_hi:[1,0,1]
	v_pk_fma_f32 v[66:67], v[178:179], v[88:89], v[66:67] op_sel_hi:[1,0,1]
	v_pk_fma_f32 v[68:69], v[180:181], v[88:89], v[68:69] op_sel_hi:[1,0,1]
	v_pk_fma_f32 v[70:71], v[182:183], v[88:89], v[70:71] op_sel_hi:[1,0,1]
	v_pk_fma_f32 v[72:73], v[184:185], v[88:89], v[72:73] op_sel_hi:[1,0,1]
	v_pk_fma_f32 v[74:75], v[186:187], v[88:89], v[74:75] op_sel_hi:[1,0,1]
	v_pk_fma_f32 v[76:77], v[188:189], v[88:89], v[76:77] op_sel_hi:[1,0,1]
	v_pk_fma_f32 v[78:79], v[190:191], v[88:89], v[78:79] op_sel_hi:[1,0,1]
	global_load_dword v88, v240, s[100:101] nt
	s_add_u32 s100, s100, 0x3000
	s_addc_u32 s101, s101, 0
	ds_read_b128 v[224:227], v9 offset:4544
	ds_read_b128 v[228:231], v9 offset:4560
	ds_read_b128 v[232:235], v9 offset:4576
	ds_read_b128 v[236:239], v9 offset:4592
	s_waitcnt vmcnt(31) lgkmcnt(8)
	v_pk_fma_f32 v[64:65], v[192:193], v[90:91], v[64:65] op_sel_hi:[1,0,1]
	v_pk_fma_f32 v[66:67], v[194:195], v[90:91], v[66:67] op_sel_hi:[1,0,1]
	v_pk_fma_f32 v[68:69], v[196:197], v[90:91], v[68:69] op_sel_hi:[1,0,1]
	v_pk_fma_f32 v[70:71], v[198:199], v[90:91], v[70:71] op_sel_hi:[1,0,1]
	v_pk_fma_f32 v[72:73], v[200:201], v[90:91], v[72:73] op_sel_hi:[1,0,1]
	v_pk_fma_f32 v[74:75], v[202:203], v[90:91], v[74:75] op_sel_hi:[1,0,1]
	v_pk_fma_f32 v[76:77], v[204:205], v[90:91], v[76:77] op_sel_hi:[1,0,1]
	v_pk_fma_f32 v[78:79], v[206:207], v[90:91], v[78:79] op_sel_hi:[1,0,1]
	global_load_dword v90, v240, s[100:101] nt
	s_add_u32 s100, s100, 0x3000
	s_addc_u32 s101, s101, 0
	ds_read_b128 v[176:179], v9 offset:4608
	ds_read_b128 v[180:183], v9 offset:4624
	ds_read_b128 v[184:187], v9 offset:4640
	ds_read_b128 v[188:191], v9 offset:4656
	s_waitcnt vmcnt(31) lgkmcnt(8)
	v_pk_fma_f32 v[64:65], v[208:209], v[92:93], v[64:65] op_sel_hi:[1,0,1]
	v_pk_fma_f32 v[66:67], v[210:211], v[92:93], v[66:67] op_sel_hi:[1,0,1]
	v_pk_fma_f32 v[68:69], v[212:213], v[92:93], v[68:69] op_sel_hi:[1,0,1]
	v_pk_fma_f32 v[70:71], v[214:215], v[92:93], v[70:71] op_sel_hi:[1,0,1]
	v_pk_fma_f32 v[72:73], v[216:217], v[92:93], v[72:73] op_sel_hi:[1,0,1]
	v_pk_fma_f32 v[74:75], v[218:219], v[92:93], v[74:75] op_sel_hi:[1,0,1]
	v_pk_fma_f32 v[76:77], v[220:221], v[92:93], v[76:77] op_sel_hi:[1,0,1]
	v_pk_fma_f32 v[78:79], v[222:223], v[92:93], v[78:79] op_sel_hi:[1,0,1]
	global_load_dword v92, v240, s[100:101] nt
	s_add_u32 s100, s100, 0x3000
	s_addc_u32 s101, s101, 0
	ds_read_b128 v[192:195], v9 offset:4672
	ds_read_b128 v[196:199], v9 offset:4688
	ds_read_b128 v[200:203], v9 offset:4704
	ds_read_b128 v[204:207], v9 offset:4720
	s_waitcnt vmcnt(31) lgkmcnt(8)
	v_pk_fma_f32 v[64:65], v[224:225], v[94:95], v[64:65] op_sel_hi:[1,0,1]
	v_pk_fma_f32 v[66:67], v[226:227], v[94:95], v[66:67] op_sel_hi:[1,0,1]
	v_pk_fma_f32 v[68:69], v[228:229], v[94:95], v[68:69] op_sel_hi:[1,0,1]
	v_pk_fma_f32 v[70:71], v[230:231], v[94:95], v[70:71] op_sel_hi:[1,0,1]
	v_pk_fma_f32 v[72:73], v[232:233], v[94:95], v[72:73] op_sel_hi:[1,0,1]
	v_pk_fma_f32 v[74:75], v[234:235], v[94:95], v[74:75] op_sel_hi:[1,0,1]
	v_pk_fma_f32 v[76:77], v[236:237], v[94:95], v[76:77] op_sel_hi:[1,0,1]
	v_pk_fma_f32 v[78:79], v[238:239], v[94:95], v[78:79] op_sel_hi:[1,0,1]
	global_load_dword v94, v240, s[100:101] nt
	s_add_u32 s100, s100, 0x3000
	s_addc_u32 s101, s101, 0
	ds_read_b128 v[208:211], v9 offset:4736
	ds_read_b128 v[212:215], v9 offset:4752
	ds_read_b128 v[216:219], v9 offset:4768
	ds_read_b128 v[220:223], v9 offset:4784
	s_waitcnt vmcnt(31) lgkmcnt(8)
	v_pk_fma_f32 v[64:65], v[176:177], v[96:97], v[64:65] op_sel_hi:[1,0,1]
	v_pk_fma_f32 v[66:67], v[178:179], v[96:97], v[66:67] op_sel_hi:[1,0,1]
	v_pk_fma_f32 v[68:69], v[180:181], v[96:97], v[68:69] op_sel_hi:[1,0,1]
	v_pk_fma_f32 v[70:71], v[182:183], v[96:97], v[70:71] op_sel_hi:[1,0,1]
	v_pk_fma_f32 v[72:73], v[184:185], v[96:97], v[72:73] op_sel_hi:[1,0,1]
	v_pk_fma_f32 v[74:75], v[186:187], v[96:97], v[74:75] op_sel_hi:[1,0,1]
	v_pk_fma_f32 v[76:77], v[188:189], v[96:97], v[76:77] op_sel_hi:[1,0,1]
	v_pk_fma_f32 v[78:79], v[190:191], v[96:97], v[78:79] op_sel_hi:[1,0,1]
	global_load_dword v96, v240, s[100:101] nt
	s_add_u32 s100, s100, 0x3000
	s_addc_u32 s101, s101, 0
	ds_read_b128 v[224:227], v9 offset:4800
	ds_read_b128 v[228:231], v9 offset:4816
	ds_read_b128 v[232:235], v9 offset:4832
	ds_read_b128 v[236:239], v9 offset:4848
	s_waitcnt vmcnt(31) lgkmcnt(8)
	v_pk_fma_f32 v[64:65], v[192:193], v[98:99], v[64:65] op_sel_hi:[1,0,1]
	v_pk_fma_f32 v[66:67], v[194:195], v[98:99], v[66:67] op_sel_hi:[1,0,1]
	v_pk_fma_f32 v[68:69], v[196:197], v[98:99], v[68:69] op_sel_hi:[1,0,1]
	v_pk_fma_f32 v[70:71], v[198:199], v[98:99], v[70:71] op_sel_hi:[1,0,1]
	v_pk_fma_f32 v[72:73], v[200:201], v[98:99], v[72:73] op_sel_hi:[1,0,1]
	v_pk_fma_f32 v[74:75], v[202:203], v[98:99], v[74:75] op_sel_hi:[1,0,1]
	v_pk_fma_f32 v[76:77], v[204:205], v[98:99], v[76:77] op_sel_hi:[1,0,1]
	v_pk_fma_f32 v[78:79], v[206:207], v[98:99], v[78:79] op_sel_hi:[1,0,1]
	global_load_dword v98, v240, s[100:101] nt
	s_add_u32 s100, s100, 0x3000
	s_addc_u32 s101, s101, 0
	ds_read_b128 v[176:179], v9 offset:4864
	ds_read_b128 v[180:183], v9 offset:4880
	ds_read_b128 v[184:187], v9 offset:4896
	ds_read_b128 v[188:191], v9 offset:4912
	s_waitcnt vmcnt(31) lgkmcnt(8)
; #define LAS __attribute__((address_space(3)))
; __device__ __forceinline__ void ada_block(const Params& p, LAS unsigned char* lds, int blk, int tid) {
;     ...
;     for (int kk = 0; kk < 128; ++kk) {
;         const float wv = __builtin_nontemporal_load(wp + (size_t)kk * 3072);
;         const LAS f32x4* cp = (const LAS f32x4*)(cs + (w * 128 + kk) * 16);
;         a0 += cp[0] * wv; a1 += cp[1] * wv; a2 += cp[2] * wv; a3 += cp[3] * wv;
;     }
	v_pk_fma_f32 v[64:65], v[208:209], v[100:101], v[64:65] op_sel_hi:[1,0,1]
	v_pk_fma_f32 v[66:67], v[210:211], v[100:101], v[66:67] op_sel_hi:[1,0,1]
	v_pk_fma_f32 v[68:69], v[212:213], v[100:101], v[68:69] op_sel_hi:[1,0,1]
	v_pk_fma_f32 v[70:71], v[214:215], v[100:101], v[70:71] op_sel_hi:[1,0,1]
	v_pk_fma_f32 v[72:73], v[216:217], v[100:101], v[72:73] op_sel_hi:[1,0,1]
	v_pk_fma_f32 v[74:75], v[218:219], v[100:101], v[74:75] op_sel_hi:[1,0,1]
	v_pk_fma_f32 v[76:77], v[220:221], v[100:101], v[76:77] op_sel_hi:[1,0,1]
	v_pk_fma_f32 v[78:79], v[222:223], v[100:101], v[78:79] op_sel_hi:[1,0,1]
	global_load_dword v100, v240, s[100:101] nt
	s_add_u32 s100, s100, 0x3000
	s_addc_u32 s101, s101, 0
	ds_read_b128 v[192:195], v9 offset:4928
	ds_read_b128 v[196:199], v9 offset:4944
	ds_read_b128 v[200:203], v9 offset:4960
	ds_read_b128 v[204:207], v9 offset:4976
	s_waitcnt vmcnt(31) lgkmcnt(8)
	v_pk_fma_f32 v[64:65], v[224:225], v[102:103], v[64:65] op_sel_hi:[1,0,1]
	v_pk_fma_f32 v[66:67], v[226:227], v[102:103], v[66:67] op_sel_hi:[1,0,1]
	v_pk_fma_f32 v[68:69], v[228:229], v[102:103], v[68:69] op_sel_hi:[1,0,1]
	v_pk_fma_f32 v[70:71], v[230:231], v[102:103], v[70:71] op_sel_hi:[1,0,1]
	v_pk_fma_f32 v[72:73], v[232:233], v[102:103], v[72:73] op_sel_hi:[1,0,1]
	v_pk_fma_f32 v[74:75], v[234:235], v[102:103], v[74:75] op_sel_hi:[1,0,1]
	v_pk_fma_f32 v[76:77], v[236:237], v[102:103], v[76:77] op_sel_hi:[1,0,1]
	v_pk_fma_f32 v[78:79], v[238:239], v[102:103], v[78:79] op_sel_hi:[1,0,1]
	global_load_dword v102, v240, s[100:101] nt
	s_add_u32 s100, s100, 0x3000
	s_addc_u32 s101, s101, 0
	ds_read_b128 v[208:211], v9 offset:4992
	ds_read_b128 v[212:215], v9 offset:5008
	ds_read_b128 v[216:219], v9 offset:5024
	ds_read_b128 v[220:223], v9 offset:5040
	s_waitcnt vmcnt(31) lgkmcnt(8)
	v_pk_fma_f32 v[64:65], v[176:177], v[104:105], v[64:65] op_sel_hi:[1,0,1]
	v_pk_fma_f32 v[66:67], v[178:179], v[104:105], v[66:67] op_sel_hi:[1,0,1]
	v_pk_fma_f32 v[68:69], v[180:181], v[104:105], v[68:69] op_sel_hi:[1,0,1]
	v_pk_fma_f32 v[70:71], v[182:183], v[104:105], v[70:71] op_sel_hi:[1,0,1]
	v_pk_fma_f32 v[72:73], v[184:185], v[104:105], v[72:73] op_sel_hi:[1,0,1]
	v_pk_fma_f32 v[74:75], v[186:187], v[104:105], v[74:75] op_sel_hi:[1,0,1]
	v_pk_fma_f32 v[76:77], v[188:189], v[104:105], v[76:77] op_sel_hi:[1,0,1]
	v_pk_fma_f32 v[78:79], v[190:191], v[104:105], v[78:79] op_sel_hi:[1,0,1]
	global_load_dword v104, v240, s[100:101] nt
	s_add_u32 s100, s100, 0x3000
	s_addc_u32 s101, s101, 0
	ds_read_b128 v[224:227], v9 offset:5056
	ds_read_b128 v[228:231], v9 offset:5072
	ds_read_b128 v[232:235], v9 offset:5088
	ds_read_b128 v[236:239], v9 offset:5104
	s_waitcnt vmcnt(31) lgkmcnt(8)
	v_pk_fma_f32 v[64:65], v[192:193], v[106:107], v[64:65] op_sel_hi:[1,0,1]
	v_pk_fma_f32 v[66:67], v[194:195], v[106:107], v[66:67] op_sel_hi:[1,0,1]
	v_pk_fma_f32 v[68:69], v[196:197], v[106:107], v[68:69] op_sel_hi:[1,0,1]
	v_pk_fma_f32 v[70:71], v[198:199], v[106:107], v[70:71] op_sel_hi:[1,0,1]
	v_pk_fma_f32 v[72:73], v[200:201], v[106:107], v[72:73] op_sel_hi:[1,0,1]
	v_pk_fma_f32 v[74:75], v[202:203], v[106:107], v[74:75] op_sel_hi:[1,0,1]
	v_pk_fma_f32 v[76:77], v[204:205], v[106:107], v[76:77] op_sel_hi:[1,0,1]
	v_pk_fma_f32 v[78:79], v[206:207], v[106:107], v[78:79] op_sel_hi:[1,0,1]
	global_load_dword v106, v240, s[100:101] nt
	s_add_u32 s100, s100, 0x3000
	s_addc_u32 s101, s101, 0
	ds_read_b128 v[176:179], v9 offset:5120
	ds_read_b128 v[180:183], v9 offset:5136
	ds_read_b128 v[184:187], v9 offset:5152
	ds_read_b128 v[188:191], v9 offset:5168
	s_waitcnt vmcnt(31) lgkmcnt(8)
	v_pk_fma_f32 v[64:65], v[208:209], v[108:109], v[64:65] op_sel_hi:[1,0,1]
	v_pk_fma_f32 v[66:67], v[210:211], v[108:109], v[66:67] op_sel_hi:[1,0,1]
	v_pk_fma_f32 v[68:69], v[212:213], v[108:109], v[68:69] op_sel_hi:[1,0,1]
	v_pk_fma_f32 v[70:71], v[214:215], v[108:109], v[70:71] op_sel_hi:[1,0,1]
	v_pk_fma_f32 v[72:73], v[216:217], v[108:109], v[72:73] op_sel_hi:[1,0,1]
	v_pk_fma_f32 v[74:75], v[218:219], v[108:109], v[74:75] op_sel_hi:[1,0,1]
	v_pk_fma_f32 v[76:77], v[220:221], v[108:109], v[76:77] op_sel_hi:[1,0,1]
	v_pk_fma_f32 v[78:79], v[222:223], v[108:109], v[78:79] op_sel_hi:[1,0,1]
	global_load_dword v108, v240, s[100:101] nt
	s_add_u32 s100, s100, 0x3000
	s_addc_u32 s101, s101, 0
	ds_read_b128 v[192:195], v9 offset:5184
	ds_read_b128 v[196:199], v9 offset:5200
	ds_read_b128 v[200:203], v9 offset:5216
	ds_read_b128 v[204:207], v9 offset:5232
	s_waitcnt vmcnt(31) lgkmcnt(8)
	v_pk_fma_f32 v[64:65], v[224:225], v[110:111], v[64:65] op_sel_hi:[1,0,1]
	v_pk_fma_f32 v[66:67], v[226:227], v[110:111], v[66:67] op_sel_hi:[1,0,1]
	v_pk_fma_f32 v[68:69], v[228:229], v[110:111], v[68:69] op_sel_hi:[1,0,1]
	v_pk_fma_f32 v[70:71], v[230:231], v[110:111], v[70:71] op_sel_hi:[1,0,1]
	v_pk_fma_f32 v[72:73], v[232:233], v[110:111], v[72:73] op_sel_hi:[1,0,1]
	v_pk_fma_f32 v[74:75], v[234:235], v[110:111], v[74:75] op_sel_hi:[1,0,1]
	v_pk_fma_f32 v[76:77], v[236:237], v[110:111], v[76:77] op_sel_hi:[1,0,1]
	v_pk_fma_f32 v[78:79], v[238:239], v[110:111], v[78:79] op_sel_hi:[1,0,1]
	global_load_dword v110, v240, s[100:101] nt
	s_add_u32 s100, s100, 0x3000
	s_addc_u32 s101, s101, 0
	ds_read_b128 v[208:211], v9 offset:5248
	ds_read_b128 v[212:215], v9 offset:5264
	ds_read_b128 v[216:219], v9 offset:5280
	ds_read_b128 v[220:223], v9 offset:5296
	s_waitcnt vmcnt(31) lgkmcnt(8)
; #define LAS __attribute__((address_space(3)))
; __device__ __forceinline__ void ada_block(const Params& p, LAS unsigned char* lds, int blk, int tid) {
;     ...
;     for (int kk = 0; kk < 128; ++kk) {
;         const float wv = __builtin_nontemporal_load(wp + (size_t)kk * 3072);
;         const LAS f32x4* cp = (const LAS f32x4*)(cs + (w * 128 + kk) * 16);
;         a0 += cp[0] * wv; a1 += cp[1] * wv; a2 += cp[2] * wv; a3 += cp[3] * wv;
;     }
	v_pk_fma_f32 v[64:65], v[176:177], v[112:113], v[64:65] op_sel_hi:[1,0,1]
	v_pk_fma_f32 v[66:67], v[178:179], v[112:113], v[66:67] op_sel_hi:[1,0,1]
	v_pk_fma_f32 v[68:69], v[180:181], v[112:113], v[68:69] op_sel_hi:[1,0,1]
	v_pk_fma_f32 v[70:71], v[182:183], v[112:113], v[70:71] op_sel_hi:[1,0,1]
	v_pk_fma_f32 v[72:73], v[184:185], v[112:113], v[72:73] op_sel_hi:[1,0,1]
	v_pk_fma_f32 v[74:75], v[186:187], v[112:113], v[74:75] op_sel_hi:[1,0,1]
	v_pk_fma_f32 v[76:77], v[188:189], v[112:113], v[76:77] op_sel_hi:[1,0,1]
	v_pk_fma_f32 v[78:79], v[190:191], v[112:113], v[78:79] op_sel_hi:[1,0,1]
	global_load_dword v112, v240, s[100:101] nt
	s_add_u32 s100, s100, 0x3000
	s_addc_u32 s101, s101, 0
	ds_read_b128 v[224:227], v9 offset:5312
	ds_read_b128 v[228:231], v9 offset:5328
	ds_read_b128 v[232:235], v9 offset:5344
	ds_read_b128 v[236:239], v9 offset:5360
	s_waitcnt vmcnt(31) lgkmcnt(8)
	v_pk_fma_f32 v[64:65], v[192:193], v[114:115], v[64:65] op_sel_hi:[1,0,1]
	v_pk_fma_f32 v[66:67], v[194:195], v[114:115], v[66:67] op_sel_hi:[1,0,1]
	v_pk_fma_f32 v[68:69], v[196:197], v[114:115], v[68:69] op_sel_hi:[1,0,1]
	v_pk_fma_f32 v[70:71], v[198:199], v[114:115], v[70:71] op_sel_hi:[1,0,1]
	v_pk_fma_f32 v[72:73], v[200:201], v[114:115], v[72:73] op_sel_hi:[1,0,1]
	v_pk_fma_f32 v[74:75], v[202:203], v[114:115], v[74:75] op_sel_hi:[1,0,1]
	v_pk_fma_f32 v[76:77], v[204:205], v[114:115], v[76:77] op_sel_hi:[1,0,1]
	v_pk_fma_f32 v[78:79], v[206:207], v[114:115], v[78:79] op_sel_hi:[1,0,1]
	global_load_dword v114, v240, s[100:101] nt
	s_add_u32 s100, s100, 0x3000
	s_addc_u32 s101, s101, 0
	ds_read_b128 v[176:179], v9 offset:5376
	ds_read_b128 v[180:183], v9 offset:5392
	ds_read_b128 v[184:187], v9 offset:5408
	ds_read_b128 v[188:191], v9 offset:5424
	s_waitcnt vmcnt(31) lgkmcnt(8)
	v_pk_fma_f32 v[64:65], v[208:209], v[116:117], v[64:65] op_sel_hi:[1,0,1]
	v_pk_fma_f32 v[66:67], v[210:211], v[116:117], v[66:67] op_sel_hi:[1,0,1]
	v_pk_fma_f32 v[68:69], v[212:213], v[116:117], v[68:69] op_sel_hi:[1,0,1]
	v_pk_fma_f32 v[70:71], v[214:215], v[116:117], v[70:71] op_sel_hi:[1,0,1]
	v_pk_fma_f32 v[72:73], v[216:217], v[116:117], v[72:73] op_sel_hi:[1,0,1]
	v_pk_fma_f32 v[74:75], v[218:219], v[116:117], v[74:75] op_sel_hi:[1,0,1]
	v_pk_fma_f32 v[76:77], v[220:221], v[116:117], v[76:77] op_sel_hi:[1,0,1]
	v_pk_fma_f32 v[78:79], v[222:223], v[116:117], v[78:79] op_sel_hi:[1,0,1]
	global_load_dword v116, v240, s[100:101] nt
	s_add_u32 s100, s100, 0x3000
	s_addc_u32 s101, s101, 0
	ds_read_b128 v[192:195], v9 offset:5440
	ds_read_b128 v[196:199], v9 offset:5456
	ds_read_b128 v[200:203], v9 offset:5472
	ds_read_b128 v[204:207], v9 offset:5488
	s_waitcnt vmcnt(31) lgkmcnt(8)
	v_pk_fma_f32 v[64:65], v[224:225], v[118:119], v[64:65] op_sel_hi:[1,0,1]
	v_pk_fma_f32 v[66:67], v[226:227], v[118:119], v[66:67] op_sel_hi:[1,0,1]
	v_pk_fma_f32 v[68:69], v[228:229], v[118:119], v[68:69] op_sel_hi:[1,0,1]
	v_pk_fma_f32 v[70:71], v[230:231], v[118:119], v[70:71] op_sel_hi:[1,0,1]
	v_pk_fma_f32 v[72:73], v[232:233], v[118:119], v[72:73] op_sel_hi:[1,0,1]
	v_pk_fma_f32 v[74:75], v[234:235], v[118:119], v[74:75] op_sel_hi:[1,0,1]
	v_pk_fma_f32 v[76:77], v[236:237], v[118:119], v[76:77] op_sel_hi:[1,0,1]
	v_pk_fma_f32 v[78:79], v[238:239], v[118:119], v[78:79] op_sel_hi:[1,0,1]
	global_load_dword v118, v240, s[100:101] nt
	s_add_u32 s100, s100, 0x3000
	s_addc_u32 s101, s101, 0
	ds_read_b128 v[208:211], v9 offset:5504
	ds_read_b128 v[212:215], v9 offset:5520
	ds_read_b128 v[216:219], v9 offset:5536
	ds_read_b128 v[220:223], v9 offset:5552
	s_waitcnt vmcnt(31) lgkmcnt(8)
	v_pk_fma_f32 v[64:65], v[176:177], v[120:121], v[64:65] op_sel_hi:[1,0,1]
	v_pk_fma_f32 v[66:67], v[178:179], v[120:121], v[66:67] op_sel_hi:[1,0,1]
	v_pk_fma_f32 v[68:69], v[180:181], v[120:121], v[68:69] op_sel_hi:[1,0,1]
	v_pk_fma_f32 v[70:71], v[182:183], v[120:121], v[70:71] op_sel_hi:[1,0,1]
	v_pk_fma_f32 v[72:73], v[184:185], v[120:121], v[72:73] op_sel_hi:[1,0,1]
	v_pk_fma_f32 v[74:75], v[186:187], v[120:121], v[74:75] op_sel_hi:[1,0,1]
	v_pk_fma_f32 v[76:77], v[188:189], v[120:121], v[76:77] op_sel_hi:[1,0,1]
	v_pk_fma_f32 v[78:79], v[190:191], v[120:121], v[78:79] op_sel_hi:[1,0,1]
	global_load_dword v120, v240, s[100:101] nt
	s_add_u32 s100, s100, 0x3000
	s_addc_u32 s101, s101, 0
	ds_read_b128 v[224:227], v9 offset:5568
	ds_read_b128 v[228:231], v9 offset:5584
	ds_read_b128 v[232:235], v9 offset:5600
	ds_read_b128 v[236:239], v9 offset:5616
	s_waitcnt vmcnt(31) lgkmcnt(8)
	v_pk_fma_f32 v[64:65], v[192:193], v[122:123], v[64:65] op_sel_hi:[1,0,1]
	v_pk_fma_f32 v[66:67], v[194:195], v[122:123], v[66:67] op_sel_hi:[1,0,1]
	v_pk_fma_f32 v[68:69], v[196:197], v[122:123], v[68:69] op_sel_hi:[1,0,1]
	v_pk_fma_f32 v[70:71], v[198:199], v[122:123], v[70:71] op_sel_hi:[1,0,1]
	v_pk_fma_f32 v[72:73], v[200:201], v[122:123], v[72:73] op_sel_hi:[1,0,1]
	v_pk_fma_f32 v[74:75], v[202:203], v[122:123], v[74:75] op_sel_hi:[1,0,1]
	v_pk_fma_f32 v[76:77], v[204:205], v[122:123], v[76:77] op_sel_hi:[1,0,1]
	v_pk_fma_f32 v[78:79], v[206:207], v[122:123], v[78:79] op_sel_hi:[1,0,1]
	global_load_dword v122, v240, s[100:101] nt
	s_add_u32 s100, s100, 0x3000
	s_addc_u32 s101, s101, 0
	ds_read_b128 v[176:179], v9 offset:5632
	ds_read_b128 v[180:183], v9 offset:5648
	ds_read_b128 v[184:187], v9 offset:5664
	ds_read_b128 v[188:191], v9 offset:5680
	s_waitcnt vmcnt(31) lgkmcnt(8)
; #define LAS __attribute__((address_space(3)))
; __device__ __forceinline__ void ada_block(const Params& p, LAS unsigned char* lds, int blk, int tid) {
;     ...
;     for (int kk = 0; kk < 128; ++kk) {
;         const float wv = __builtin_nontemporal_load(wp + (size_t)kk * 3072);
;         const LAS f32x4* cp = (const LAS f32x4*)(cs + (w * 128 + kk) * 16);
;         a0 += cp[0] * wv; a1 += cp[1] * wv; a2 += cp[2] * wv; a3 += cp[3] * wv;
;     }
	v_pk_fma_f32 v[64:65], v[208:209], v[124:125], v[64:65] op_sel_hi:[1,0,1]
	v_pk_fma_f32 v[66:67], v[210:211], v[124:125], v[66:67] op_sel_hi:[1,0,1]
	v_pk_fma_f32 v[68:69], v[212:213], v[124:125], v[68:69] op_sel_hi:[1,0,1]
	v_pk_fma_f32 v[70:71], v[214:215], v[124:125], v[70:71] op_sel_hi:[1,0,1]
	v_pk_fma_f32 v[72:73], v[216:217], v[124:125], v[72:73] op_sel_hi:[1,0,1]
	v_pk_fma_f32 v[74:75], v[218:219], v[124:125], v[74:75] op_sel_hi:[1,0,1]
	v_pk_fma_f32 v[76:77], v[220:221], v[124:125], v[76:77] op_sel_hi:[1,0,1]
	v_pk_fma_f32 v[78:79], v[222:223], v[124:125], v[78:79] op_sel_hi:[1,0,1]
	global_load_dword v124, v240, s[100:101] nt
	s_add_u32 s100, s100, 0x3000
	s_addc_u32 s101, s101, 0
	ds_read_b128 v[192:195], v9 offset:5696
	ds_read_b128 v[196:199], v9 offset:5712
	ds_read_b128 v[200:203], v9 offset:5728
	ds_read_b128 v[204:207], v9 offset:5744
	s_waitcnt vmcnt(31) lgkmcnt(8)
	v_pk_fma_f32 v[64:65], v[224:225], v[126:127], v[64:65] op_sel_hi:[1,0,1]
	v_pk_fma_f32 v[66:67], v[226:227], v[126:127], v[66:67] op_sel_hi:[1,0,1]
	v_pk_fma_f32 v[68:69], v[228:229], v[126:127], v[68:69] op_sel_hi:[1,0,1]
	v_pk_fma_f32 v[70:71], v[230:231], v[126:127], v[70:71] op_sel_hi:[1,0,1]
	v_pk_fma_f32 v[72:73], v[232:233], v[126:127], v[72:73] op_sel_hi:[1,0,1]
	v_pk_fma_f32 v[74:75], v[234:235], v[126:127], v[74:75] op_sel_hi:[1,0,1]
	v_pk_fma_f32 v[76:77], v[236:237], v[126:127], v[76:77] op_sel_hi:[1,0,1]
	v_pk_fma_f32 v[78:79], v[238:239], v[126:127], v[78:79] op_sel_hi:[1,0,1]
	global_load_dword v126, v240, s[100:101] nt
	s_add_u32 s100, s100, 0x3000
	s_addc_u32 s101, s101, 0
	ds_read_b128 v[208:211], v9 offset:5760
	ds_read_b128 v[212:215], v9 offset:5776
	ds_read_b128 v[216:219], v9 offset:5792
	ds_read_b128 v[220:223], v9 offset:5808
	s_waitcnt vmcnt(31) lgkmcnt(8)
	v_pk_fma_f32 v[64:65], v[176:177], v[128:129], v[64:65] op_sel_hi:[1,0,1]
	v_pk_fma_f32 v[66:67], v[178:179], v[128:129], v[66:67] op_sel_hi:[1,0,1]
	v_pk_fma_f32 v[68:69], v[180:181], v[128:129], v[68:69] op_sel_hi:[1,0,1]
	v_pk_fma_f32 v[70:71], v[182:183], v[128:129], v[70:71] op_sel_hi:[1,0,1]
	v_pk_fma_f32 v[72:73], v[184:185], v[128:129], v[72:73] op_sel_hi:[1,0,1]
	v_pk_fma_f32 v[74:75], v[186:187], v[128:129], v[74:75] op_sel_hi:[1,0,1]
	v_pk_fma_f32 v[76:77], v[188:189], v[128:129], v[76:77] op_sel_hi:[1,0,1]
	v_pk_fma_f32 v[78:79], v[190:191], v[128:129], v[78:79] op_sel_hi:[1,0,1]
	global_load_dword v128, v240, s[100:101] nt
	s_add_u32 s100, s100, 0x3000
	s_addc_u32 s101, s101, 0
	ds_read_b128 v[224:227], v9 offset:5824
	ds_read_b128 v[228:231], v9 offset:5840
	ds_read_b128 v[232:235], v9 offset:5856
	ds_read_b128 v[236:239], v9 offset:5872
	s_waitcnt vmcnt(31) lgkmcnt(8)
	v_pk_fma_f32 v[64:65], v[192:193], v[130:131], v[64:65] op_sel_hi:[1,0,1]
	v_pk_fma_f32 v[66:67], v[194:195], v[130:131], v[66:67] op_sel_hi:[1,0,1]
	v_pk_fma_f32 v[68:69], v[196:197], v[130:131], v[68:69] op_sel_hi:[1,0,1]
	v_pk_fma_f32 v[70:71], v[198:199], v[130:131], v[70:71] op_sel_hi:[1,0,1]
	v_pk_fma_f32 v[72:73], v[200:201], v[130:131], v[72:73] op_sel_hi:[1,0,1]
	v_pk_fma_f32 v[74:75], v[202:203], v[130:131], v[74:75] op_sel_hi:[1,0,1]
	v_pk_fma_f32 v[76:77], v[204:205], v[130:131], v[76:77] op_sel_hi:[1,0,1]
	v_pk_fma_f32 v[78:79], v[206:207], v[130:131], v[78:79] op_sel_hi:[1,0,1]
	global_load_dword v130, v240, s[100:101] nt
	s_add_u32 s100, s100, 0x3000
	s_addc_u32 s101, s101, 0
	ds_read_b128 v[176:179], v9 offset:5888
	ds_read_b128 v[180:183], v9 offset:5904
	ds_read_b128 v[184:187], v9 offset:5920
	ds_read_b128 v[188:191], v9 offset:5936
	s_waitcnt vmcnt(31) lgkmcnt(8)
	v_pk_fma_f32 v[64:65], v[208:209], v[132:133], v[64:65] op_sel_hi:[1,0,1]
	v_pk_fma_f32 v[66:67], v[210:211], v[132:133], v[66:67] op_sel_hi:[1,0,1]
	v_pk_fma_f32 v[68:69], v[212:213], v[132:133], v[68:69] op_sel_hi:[1,0,1]
	v_pk_fma_f32 v[70:71], v[214:215], v[132:133], v[70:71] op_sel_hi:[1,0,1]
	v_pk_fma_f32 v[72:73], v[216:217], v[132:133], v[72:73] op_sel_hi:[1,0,1]
	v_pk_fma_f32 v[74:75], v[218:219], v[132:133], v[74:75] op_sel_hi:[1,0,1]
	v_pk_fma_f32 v[76:77], v[220:221], v[132:133], v[76:77] op_sel_hi:[1,0,1]
	v_pk_fma_f32 v[78:79], v[222:223], v[132:133], v[78:79] op_sel_hi:[1,0,1]
	global_load_dword v132, v240, s[100:101] nt
	s_add_u32 s100, s100, 0x3000
	s_addc_u32 s101, s101, 0
	ds_read_b128 v[192:195], v9 offset:5952
	ds_read_b128 v[196:199], v9 offset:5968
	ds_read_b128 v[200:203], v9 offset:5984
	ds_read_b128 v[204:207], v9 offset:6000
	s_waitcnt vmcnt(31) lgkmcnt(8)
	v_pk_fma_f32 v[64:65], v[224:225], v[134:135], v[64:65] op_sel_hi:[1,0,1]
	v_pk_fma_f32 v[66:67], v[226:227], v[134:135], v[66:67] op_sel_hi:[1,0,1]
	v_pk_fma_f32 v[68:69], v[228:229], v[134:135], v[68:69] op_sel_hi:[1,0,1]
	v_pk_fma_f32 v[70:71], v[230:231], v[134:135], v[70:71] op_sel_hi:[1,0,1]
	v_pk_fma_f32 v[72:73], v[232:233], v[134:135], v[72:73] op_sel_hi:[1,0,1]
	v_pk_fma_f32 v[74:75], v[234:235], v[134:135], v[74:75] op_sel_hi:[1,0,1]
	v_pk_fma_f32 v[76:77], v[236:237], v[134:135], v[76:77] op_sel_hi:[1,0,1]
	v_pk_fma_f32 v[78:79], v[238:239], v[134:135], v[78:79] op_sel_hi:[1,0,1]
	global_load_dword v134, v240, s[100:101] nt
	s_add_u32 s100, s100, 0x3000
	s_addc_u32 s101, s101, 0
	ds_read_b128 v[208:211], v9 offset:6016
	ds_read_b128 v[212:215], v9 offset:6032
	ds_read_b128 v[216:219], v9 offset:6048
	ds_read_b128 v[220:223], v9 offset:6064
	s_waitcnt vmcnt(31) lgkmcnt(8)
; #define LAS __attribute__((address_space(3)))
; __device__ __forceinline__ void ada_block(const Params& p, LAS unsigned char* lds, int blk, int tid) {
;     ...
;     for (int kk = 0; kk < 128; ++kk) {
;         const float wv = __builtin_nontemporal_load(wp + (size_t)kk * 3072);
;         const LAS f32x4* cp = (const LAS f32x4*)(cs + (w * 128 + kk) * 16);
;         a0 += cp[0] * wv; a1 += cp[1] * wv; a2 += cp[2] * wv; a3 += cp[3] * wv;
	v_pk_fma_f32 v[64:65], v[176:177], v[136:137], v[64:65] op_sel_hi:[1,0,1]
	v_pk_fma_f32 v[66:67], v[178:179], v[136:137], v[66:67] op_sel_hi:[1,0,1]
	v_pk_fma_f32 v[68:69], v[180:181], v[136:137], v[68:69] op_sel_hi:[1,0,1]
	v_pk_fma_f32 v[70:71], v[182:183], v[136:137], v[70:71] op_sel_hi:[1,0,1]
	v_pk_fma_f32 v[72:73], v[184:185], v[136:137], v[72:73] op_sel_hi:[1,0,1]
	v_pk_fma_f32 v[74:75], v[186:187], v[136:137], v[74:75] op_sel_hi:[1,0,1]
	v_pk_fma_f32 v[76:77], v[188:189], v[136:137], v[76:77] op_sel_hi:[1,0,1]
	v_pk_fma_f32 v[78:79], v[190:191], v[136:137], v[78:79] op_sel_hi:[1,0,1]
	global_load_dword v136, v240, s[100:101] nt
	s_add_u32 s100, s100, 0x3000
	s_addc_u32 s101, s101, 0
	ds_read_b128 v[224:227], v9 offset:6080
	ds_read_b128 v[228:231], v9 offset:6096
	ds_read_b128 v[232:235], v9 offset:6112
	ds_read_b128 v[236:239], v9 offset:6128
	s_waitcnt vmcnt(31) lgkmcnt(8)
	v_pk_fma_f32 v[64:65], v[192:193], v[138:139], v[64:65] op_sel_hi:[1,0,1]
	v_pk_fma_f32 v[66:67], v[194:195], v[138:139], v[66:67] op_sel_hi:[1,0,1]
	v_pk_fma_f32 v[68:69], v[196:197], v[138:139], v[68:69] op_sel_hi:[1,0,1]
	v_pk_fma_f32 v[70:71], v[198:199], v[138:139], v[70:71] op_sel_hi:[1,0,1]
	v_pk_fma_f32 v[72:73], v[200:201], v[138:139], v[72:73] op_sel_hi:[1,0,1]
	v_pk_fma_f32 v[74:75], v[202:203], v[138:139], v[74:75] op_sel_hi:[1,0,1]
	v_pk_fma_f32 v[76:77], v[204:205], v[138:139], v[76:77] op_sel_hi:[1,0,1]
	v_pk_fma_f32 v[78:79], v[206:207], v[138:139], v[78:79] op_sel_hi:[1,0,1]
	global_load_dword v138, v240, s[100:101] nt
	s_add_u32 s100, s100, 0x3000
	s_addc_u32 s101, s101, 0
	ds_read_b128 v[176:179], v9 offset:6144
	ds_read_b128 v[180:183], v9 offset:6160
	ds_read_b128 v[184:187], v9 offset:6176
	ds_read_b128 v[188:191], v9 offset:6192
	s_waitcnt vmcnt(31) lgkmcnt(8)
	v_pk_fma_f32 v[64:65], v[208:209], v[140:141], v[64:65] op_sel_hi:[1,0,1]
	v_pk_fma_f32 v[66:67], v[210:211], v[140:141], v[66:67] op_sel_hi:[1,0,1]
	v_pk_fma_f32 v[68:69], v[212:213], v[140:141], v[68:69] op_sel_hi:[1,0,1]
	v_pk_fma_f32 v[70:71], v[214:215], v[140:141], v[70:71] op_sel_hi:[1,0,1]
	v_pk_fma_f32 v[72:73], v[216:217], v[140:141], v[72:73] op_sel_hi:[1,0,1]
	v_pk_fma_f32 v[74:75], v[218:219], v[140:141], v[74:75] op_sel_hi:[1,0,1]
	v_pk_fma_f32 v[76:77], v[220:221], v[140:141], v[76:77] op_sel_hi:[1,0,1]
	v_pk_fma_f32 v[78:79], v[222:223], v[140:141], v[78:79] op_sel_hi:[1,0,1]
	global_load_dword v140, v240, s[100:101] nt
	s_add_u32 s100, s100, 0x3000
	s_addc_u32 s101, s101, 0
	ds_read_b128 v[192:195], v9 offset:6208
	ds_read_b128 v[196:199], v9 offset:6224
	ds_read_b128 v[200:203], v9 offset:6240
	ds_read_b128 v[204:207], v9 offset:6256
	s_waitcnt vmcnt(31) lgkmcnt(8)
	v_pk_fma_f32 v[64:65], v[224:225], v[142:143], v[64:65] op_sel_hi:[1,0,1]
	v_pk_fma_f32 v[66:67], v[226:227], v[142:143], v[66:67] op_sel_hi:[1,0,1]
	v_pk_fma_f32 v[68:69], v[228:229], v[142:143], v[68:69] op_sel_hi:[1,0,1]
	v_pk_fma_f32 v[70:71], v[230:231], v[142:143], v[70:71] op_sel_hi:[1,0,1]
	v_pk_fma_f32 v[72:73], v[232:233], v[142:143], v[72:73] op_sel_hi:[1,0,1]
	v_pk_fma_f32 v[74:75], v[234:235], v[142:143], v[74:75] op_sel_hi:[1,0,1]
	v_pk_fma_f32 v[76:77], v[236:237], v[142:143], v[76:77] op_sel_hi:[1,0,1]
	v_pk_fma_f32 v[78:79], v[238:239], v[142:143], v[78:79] op_sel_hi:[1,0,1]
	global_load_dword v142, v240, s[100:101] nt
	s_add_u32 s100, s100, 0x3000
	s_addc_u32 s101, s101, 0
	ds_read_b128 v[208:211], v9 offset:6272
	ds_read_b128 v[212:215], v9 offset:6288
	ds_read_b128 v[216:219], v9 offset:6304
	ds_read_b128 v[220:223], v9 offset:6320
	s_waitcnt vmcnt(31) lgkmcnt(8)
	v_pk_fma_f32 v[64:65], v[176:177], v[80:81], v[64:65] op_sel_hi:[1,0,1]
	v_pk_fma_f32 v[66:67], v[178:179], v[80:81], v[66:67] op_sel_hi:[1,0,1]
	v_pk_fma_f32 v[68:69], v[180:181], v[80:81], v[68:69] op_sel_hi:[1,0,1]
	v_pk_fma_f32 v[70:71], v[182:183], v[80:81], v[70:71] op_sel_hi:[1,0,1]
	v_pk_fma_f32 v[72:73], v[184:185], v[80:81], v[72:73] op_sel_hi:[1,0,1]
	v_pk_fma_f32 v[74:75], v[186:187], v[80:81], v[74:75] op_sel_hi:[1,0,1]
	v_pk_fma_f32 v[76:77], v[188:189], v[80:81], v[76:77] op_sel_hi:[1,0,1]
	v_pk_fma_f32 v[78:79], v[190:191], v[80:81], v[78:79] op_sel_hi:[1,0,1]
	ds_read_b128 v[224:227], v9 offset:6336
	ds_read_b128 v[228:231], v9 offset:6352
	ds_read_b128 v[232:235], v9 offset:6368
	ds_read_b128 v[236:239], v9 offset:6384
	s_waitcnt vmcnt(30) lgkmcnt(8)
	v_pk_fma_f32 v[64:65], v[192:193], v[82:83], v[64:65] op_sel_hi:[1,0,1]
	v_pk_fma_f32 v[66:67], v[194:195], v[82:83], v[66:67] op_sel_hi:[1,0,1]
	v_pk_fma_f32 v[68:69], v[196:197], v[82:83], v[68:69] op_sel_hi:[1,0,1]
	v_pk_fma_f32 v[70:71], v[198:199], v[82:83], v[70:71] op_sel_hi:[1,0,1]
	v_pk_fma_f32 v[72:73], v[200:201], v[82:83], v[72:73] op_sel_hi:[1,0,1]
	v_pk_fma_f32 v[74:75], v[202:203], v[82:83], v[74:75] op_sel_hi:[1,0,1]
	v_pk_fma_f32 v[76:77], v[204:205], v[82:83], v[76:77] op_sel_hi:[1,0,1]
	v_pk_fma_f32 v[78:79], v[206:207], v[82:83], v[78:79] op_sel_hi:[1,0,1]
	ds_read_b128 v[176:179], v9 offset:6400
	ds_read_b128 v[180:183], v9 offset:6416
	ds_read_b128 v[184:187], v9 offset:6432
	ds_read_b128 v[188:191], v9 offset:6448
	s_waitcnt vmcnt(29) lgkmcnt(8)
	v_pk_fma_f32 v[64:65], v[208:209], v[84:85], v[64:65] op_sel_hi:[1,0,1]
	v_pk_fma_f32 v[66:67], v[210:211], v[84:85], v[66:67] op_sel_hi:[1,0,1]
	v_pk_fma_f32 v[68:69], v[212:213], v[84:85], v[68:69] op_sel_hi:[1,0,1]
	v_pk_fma_f32 v[70:71], v[214:215], v[84:85], v[70:71] op_sel_hi:[1,0,1]
	v_pk_fma_f32 v[72:73], v[216:217], v[84:85], v[72:73] op_sel_hi:[1,0,1]
	v_pk_fma_f32 v[74:75], v[218:219], v[84:85], v[74:75] op_sel_hi:[1,0,1]
	v_pk_fma_f32 v[76:77], v[220:221], v[84:85], v[76:77] op_sel_hi:[1,0,1]
	v_pk_fma_f32 v[78:79], v[222:223], v[84:85], v[78:79] op_sel_hi:[1,0,1]
	ds_read_b128 v[192:195], v9 offset:6464
	ds_read_b128 v[196:199], v9 offset:6480
	ds_read_b128 v[200:203], v9 offset:6496
	ds_read_b128 v[204:207], v9 offset:6512
	s_waitcnt vmcnt(28) lgkmcnt(8)
; #define LAS __attribute__((address_space(3)))
; __device__ __forceinline__ void ada_block(const Params& p, LAS unsigned char* lds, int blk, int tid) {
;     ...
;     for (int kk = 0; kk < 128; ++kk) {
;         const float wv = __builtin_nontemporal_load(wp + (size_t)kk * 3072);
;         const LAS f32x4* cp = (const LAS f32x4*)(cs + (w * 128 + kk) * 16);
;         a0 += cp[0] * wv; a1 += cp[1] * wv; a2 += cp[2] * wv; a3 += cp[3] * wv;
	v_pk_fma_f32 v[64:65], v[224:225], v[86:87], v[64:65] op_sel_hi:[1,0,1]
	v_pk_fma_f32 v[66:67], v[226:227], v[86:87], v[66:67] op_sel_hi:[1,0,1]
	v_pk_fma_f32 v[68:69], v[228:229], v[86:87], v[68:69] op_sel_hi:[1,0,1]
	v_pk_fma_f32 v[70:71], v[230:231], v[86:87], v[70:71] op_sel_hi:[1,0,1]
	v_pk_fma_f32 v[72:73], v[232:233], v[86:87], v[72:73] op_sel_hi:[1,0,1]
	v_pk_fma_f32 v[74:75], v[234:235], v[86:87], v[74:75] op_sel_hi:[1,0,1]
	v_pk_fma_f32 v[76:77], v[236:237], v[86:87], v[76:77] op_sel_hi:[1,0,1]
	v_pk_fma_f32 v[78:79], v[238:239], v[86:87], v[78:79] op_sel_hi:[1,0,1]
	ds_read_b128 v[208:211], v9 offset:6528
	ds_read_b128 v[212:215], v9 offset:6544
	ds_read_b128 v[216:219], v9 offset:6560
	ds_read_b128 v[220:223], v9 offset:6576
	s_waitcnt vmcnt(27) lgkmcnt(8)
	v_pk_fma_f32 v[64:65], v[176:177], v[88:89], v[64:65] op_sel_hi:[1,0,1]
	v_pk_fma_f32 v[66:67], v[178:179], v[88:89], v[66:67] op_sel_hi:[1,0,1]
	v_pk_fma_f32 v[68:69], v[180:181], v[88:89], v[68:69] op_sel_hi:[1,0,1]
	v_pk_fma_f32 v[70:71], v[182:183], v[88:89], v[70:71] op_sel_hi:[1,0,1]
	v_pk_fma_f32 v[72:73], v[184:185], v[88:89], v[72:73] op_sel_hi:[1,0,1]
	v_pk_fma_f32 v[74:75], v[186:187], v[88:89], v[74:75] op_sel_hi:[1,0,1]
	v_pk_fma_f32 v[76:77], v[188:189], v[88:89], v[76:77] op_sel_hi:[1,0,1]
	v_pk_fma_f32 v[78:79], v[190:191], v[88:89], v[78:79] op_sel_hi:[1,0,1]
	ds_read_b128 v[224:227], v9 offset:6592
	ds_read_b128 v[228:231], v9 offset:6608
	ds_read_b128 v[232:235], v9 offset:6624
	ds_read_b128 v[236:239], v9 offset:6640
	s_waitcnt vmcnt(26) lgkmcnt(8)
	v_pk_fma_f32 v[64:65], v[192:193], v[90:91], v[64:65] op_sel_hi:[1,0,1]
	v_pk_fma_f32 v[66:67], v[194:195], v[90:91], v[66:67] op_sel_hi:[1,0,1]
	v_pk_fma_f32 v[68:69], v[196:197], v[90:91], v[68:69] op_sel_hi:[1,0,1]
	v_pk_fma_f32 v[70:71], v[198:199], v[90:91], v[70:71] op_sel_hi:[1,0,1]
	v_pk_fma_f32 v[72:73], v[200:201], v[90:91], v[72:73] op_sel_hi:[1,0,1]
	v_pk_fma_f32 v[74:75], v[202:203], v[90:91], v[74:75] op_sel_hi:[1,0,1]
	v_pk_fma_f32 v[76:77], v[204:205], v[90:91], v[76:77] op_sel_hi:[1,0,1]
	v_pk_fma_f32 v[78:79], v[206:207], v[90:91], v[78:79] op_sel_hi:[1,0,1]
	ds_read_b128 v[176:179], v9 offset:6656
	ds_read_b128 v[180:183], v9 offset:6672
	ds_read_b128 v[184:187], v9 offset:6688
	ds_read_b128 v[188:191], v9 offset:6704
	s_waitcnt vmcnt(25) lgkmcnt(8)
	v_pk_fma_f32 v[64:65], v[208:209], v[92:93], v[64:65] op_sel_hi:[1,0,1]
	v_pk_fma_f32 v[66:67], v[210:211], v[92:93], v[66:67] op_sel_hi:[1,0,1]
	v_pk_fma_f32 v[68:69], v[212:213], v[92:93], v[68:69] op_sel_hi:[1,0,1]
	v_pk_fma_f32 v[70:71], v[214:215], v[92:93], v[70:71] op_sel_hi:[1,0,1]
	v_pk_fma_f32 v[72:73], v[216:217], v[92:93], v[72:73] op_sel_hi:[1,0,1]
	v_pk_fma_f32 v[74:75], v[218:219], v[92:93], v[74:75] op_sel_hi:[1,0,1]
	v_pk_fma_f32 v[76:77], v[220:221], v[92:93], v[76:77] op_sel_hi:[1,0,1]
	v_pk_fma_f32 v[78:79], v[222:223], v[92:93], v[78:79] op_sel_hi:[1,0,1]
	ds_read_b128 v[192:195], v9 offset:6720
	ds_read_b128 v[196:199], v9 offset:6736
	ds_read_b128 v[200:203], v9 offset:6752
	ds_read_b128 v[204:207], v9 offset:6768
	s_waitcnt vmcnt(24) lgkmcnt(8)
	v_pk_fma_f32 v[64:65], v[224:225], v[94:95], v[64:65] op_sel_hi:[1,0,1]
	v_pk_fma_f32 v[66:67], v[226:227], v[94:95], v[66:67] op_sel_hi:[1,0,1]
	v_pk_fma_f32 v[68:69], v[228:229], v[94:95], v[68:69] op_sel_hi:[1,0,1]
	v_pk_fma_f32 v[70:71], v[230:231], v[94:95], v[70:71] op_sel_hi:[1,0,1]
	v_pk_fma_f32 v[72:73], v[232:233], v[94:95], v[72:73] op_sel_hi:[1,0,1]
	v_pk_fma_f32 v[74:75], v[234:235], v[94:95], v[74:75] op_sel_hi:[1,0,1]
	v_pk_fma_f32 v[76:77], v[236:237], v[94:95], v[76:77] op_sel_hi:[1,0,1]
	v_pk_fma_f32 v[78:79], v[238:239], v[94:95], v[78:79] op_sel_hi:[1,0,1]
	ds_read_b128 v[208:211], v9 offset:6784
	ds_read_b128 v[212:215], v9 offset:6800
	ds_read_b128 v[216:219], v9 offset:6816
	ds_read_b128 v[220:223], v9 offset:6832
	s_waitcnt vmcnt(23) lgkmcnt(8)
	v_pk_fma_f32 v[64:65], v[176:177], v[96:97], v[64:65] op_sel_hi:[1,0,1]
	v_pk_fma_f32 v[66:67], v[178:179], v[96:97], v[66:67] op_sel_hi:[1,0,1]
	v_pk_fma_f32 v[68:69], v[180:181], v[96:97], v[68:69] op_sel_hi:[1,0,1]
	v_pk_fma_f32 v[70:71], v[182:183], v[96:97], v[70:71] op_sel_hi:[1,0,1]
	v_pk_fma_f32 v[72:73], v[184:185], v[96:97], v[72:73] op_sel_hi:[1,0,1]
	v_pk_fma_f32 v[74:75], v[186:187], v[96:97], v[74:75] op_sel_hi:[1,0,1]
	v_pk_fma_f32 v[76:77], v[188:189], v[96:97], v[76:77] op_sel_hi:[1,0,1]
	v_pk_fma_f32 v[78:79], v[190:191], v[96:97], v[78:79] op_sel_hi:[1,0,1]
	ds_read_b128 v[224:227], v9 offset:6848
	ds_read_b128 v[228:231], v9 offset:6864
	ds_read_b128 v[232:235], v9 offset:6880
	ds_read_b128 v[236:239], v9 offset:6896
	s_waitcnt vmcnt(22) lgkmcnt(8)
	v_pk_fma_f32 v[64:65], v[192:193], v[98:99], v[64:65] op_sel_hi:[1,0,1]
	v_pk_fma_f32 v[66:67], v[194:195], v[98:99], v[66:67] op_sel_hi:[1,0,1]
	v_pk_fma_f32 v[68:69], v[196:197], v[98:99], v[68:69] op_sel_hi:[1,0,1]
	v_pk_fma_f32 v[70:71], v[198:199], v[98:99], v[70:71] op_sel_hi:[1,0,1]
	v_pk_fma_f32 v[72:73], v[200:201], v[98:99], v[72:73] op_sel_hi:[1,0,1]
	v_pk_fma_f32 v[74:75], v[202:203], v[98:99], v[74:75] op_sel_hi:[1,0,1]
	v_pk_fma_f32 v[76:77], v[204:205], v[98:99], v[76:77] op_sel_hi:[1,0,1]
	v_pk_fma_f32 v[78:79], v[206:207], v[98:99], v[78:79] op_sel_hi:[1,0,1]
	ds_read_b128 v[176:179], v9 offset:6912
	ds_read_b128 v[180:183], v9 offset:6928
	ds_read_b128 v[184:187], v9 offset:6944
	ds_read_b128 v[188:191], v9 offset:6960
	s_waitcnt vmcnt(21) lgkmcnt(8)
; #define LAS __attribute__((address_space(3)))
; __device__ __forceinline__ void ada_block(const Params& p, LAS unsigned char* lds, int blk, int tid) {
;     ...
;     for (int kk = 0; kk < 128; ++kk) {
;         const float wv = __builtin_nontemporal_load(wp + (size_t)kk * 3072);
;         const LAS f32x4* cp = (const LAS f32x4*)(cs + (w * 128 + kk) * 16);
;         a0 += cp[0] * wv; a1 += cp[1] * wv; a2 += cp[2] * wv; a3 += cp[3] * wv;
	v_pk_fma_f32 v[64:65], v[208:209], v[100:101], v[64:65] op_sel_hi:[1,0,1]
	v_pk_fma_f32 v[66:67], v[210:211], v[100:101], v[66:67] op_sel_hi:[1,0,1]
	v_pk_fma_f32 v[68:69], v[212:213], v[100:101], v[68:69] op_sel_hi:[1,0,1]
	v_pk_fma_f32 v[70:71], v[214:215], v[100:101], v[70:71] op_sel_hi:[1,0,1]
	v_pk_fma_f32 v[72:73], v[216:217], v[100:101], v[72:73] op_sel_hi:[1,0,1]
	v_pk_fma_f32 v[74:75], v[218:219], v[100:101], v[74:75] op_sel_hi:[1,0,1]
	v_pk_fma_f32 v[76:77], v[220:221], v[100:101], v[76:77] op_sel_hi:[1,0,1]
	v_pk_fma_f32 v[78:79], v[222:223], v[100:101], v[78:79] op_sel_hi:[1,0,1]
	ds_read_b128 v[192:195], v9 offset:6976
	ds_read_b128 v[196:199], v9 offset:6992
	ds_read_b128 v[200:203], v9 offset:7008
	ds_read_b128 v[204:207], v9 offset:7024
	s_waitcnt vmcnt(20) lgkmcnt(8)
	v_pk_fma_f32 v[64:65], v[224:225], v[102:103], v[64:65] op_sel_hi:[1,0,1]
	v_pk_fma_f32 v[66:67], v[226:227], v[102:103], v[66:67] op_sel_hi:[1,0,1]
	v_pk_fma_f32 v[68:69], v[228:229], v[102:103], v[68:69] op_sel_hi:[1,0,1]
	v_pk_fma_f32 v[70:71], v[230:231], v[102:103], v[70:71] op_sel_hi:[1,0,1]
	v_pk_fma_f32 v[72:73], v[232:233], v[102:103], v[72:73] op_sel_hi:[1,0,1]
	v_pk_fma_f32 v[74:75], v[234:235], v[102:103], v[74:75] op_sel_hi:[1,0,1]
	v_pk_fma_f32 v[76:77], v[236:237], v[102:103], v[76:77] op_sel_hi:[1,0,1]
	v_pk_fma_f32 v[78:79], v[238:239], v[102:103], v[78:79] op_sel_hi:[1,0,1]
	ds_read_b128 v[208:211], v9 offset:7040
	ds_read_b128 v[212:215], v9 offset:7056
	ds_read_b128 v[216:219], v9 offset:7072
	ds_read_b128 v[220:223], v9 offset:7088
	s_waitcnt vmcnt(19) lgkmcnt(8)
	v_pk_fma_f32 v[64:65], v[176:177], v[104:105], v[64:65] op_sel_hi:[1,0,1]
	v_pk_fma_f32 v[66:67], v[178:179], v[104:105], v[66:67] op_sel_hi:[1,0,1]
	v_pk_fma_f32 v[68:69], v[180:181], v[104:105], v[68:69] op_sel_hi:[1,0,1]
	v_pk_fma_f32 v[70:71], v[182:183], v[104:105], v[70:71] op_sel_hi:[1,0,1]
	v_pk_fma_f32 v[72:73], v[184:185], v[104:105], v[72:73] op_sel_hi:[1,0,1]
	v_pk_fma_f32 v[74:75], v[186:187], v[104:105], v[74:75] op_sel_hi:[1,0,1]
	v_pk_fma_f32 v[76:77], v[188:189], v[104:105], v[76:77] op_sel_hi:[1,0,1]
	v_pk_fma_f32 v[78:79], v[190:191], v[104:105], v[78:79] op_sel_hi:[1,0,1]
	ds_read_b128 v[224:227], v9 offset:7104
	ds_read_b128 v[228:231], v9 offset:7120
	ds_read_b128 v[232:235], v9 offset:7136
	ds_read_b128 v[236:239], v9 offset:7152
	s_waitcnt vmcnt(18) lgkmcnt(8)
	v_pk_fma_f32 v[64:65], v[192:193], v[106:107], v[64:65] op_sel_hi:[1,0,1]
	v_pk_fma_f32 v[66:67], v[194:195], v[106:107], v[66:67] op_sel_hi:[1,0,1]
	v_pk_fma_f32 v[68:69], v[196:197], v[106:107], v[68:69] op_sel_hi:[1,0,1]
	v_pk_fma_f32 v[70:71], v[198:199], v[106:107], v[70:71] op_sel_hi:[1,0,1]
	v_pk_fma_f32 v[72:73], v[200:201], v[106:107], v[72:73] op_sel_hi:[1,0,1]
	v_pk_fma_f32 v[74:75], v[202:203], v[106:107], v[74:75] op_sel_hi:[1,0,1]
	v_pk_fma_f32 v[76:77], v[204:205], v[106:107], v[76:77] op_sel_hi:[1,0,1]
	v_pk_fma_f32 v[78:79], v[206:207], v[106:107], v[78:79] op_sel_hi:[1,0,1]
	ds_read_b128 v[176:179], v9 offset:7168
	ds_read_b128 v[180:183], v9 offset:7184
	ds_read_b128 v[184:187], v9 offset:7200
	ds_read_b128 v[188:191], v9 offset:7216
	s_waitcnt vmcnt(17) lgkmcnt(8)
	v_pk_fma_f32 v[64:65], v[208:209], v[108:109], v[64:65] op_sel_hi:[1,0,1]
	v_pk_fma_f32 v[66:67], v[210:211], v[108:109], v[66:67] op_sel_hi:[1,0,1]
	v_pk_fma_f32 v[68:69], v[212:213], v[108:109], v[68:69] op_sel_hi:[1,0,1]
	v_pk_fma_f32 v[70:71], v[214:215], v[108:109], v[70:71] op_sel_hi:[1,0,1]
	v_pk_fma_f32 v[72:73], v[216:217], v[108:109], v[72:73] op_sel_hi:[1,0,1]
	v_pk_fma_f32 v[74:75], v[218:219], v[108:109], v[74:75] op_sel_hi:[1,0,1]
	v_pk_fma_f32 v[76:77], v[220:221], v[108:109], v[76:77] op_sel_hi:[1,0,1]
	v_pk_fma_f32 v[78:79], v[222:223], v[108:109], v[78:79] op_sel_hi:[1,0,1]
	ds_read_b128 v[192:195], v9 offset:7232
	ds_read_b128 v[196:199], v9 offset:7248
	ds_read_b128 v[200:203], v9 offset:7264
	ds_read_b128 v[204:207], v9 offset:7280
	s_waitcnt vmcnt(16) lgkmcnt(8)
	v_pk_fma_f32 v[64:65], v[224:225], v[110:111], v[64:65] op_sel_hi:[1,0,1]
	v_pk_fma_f32 v[66:67], v[226:227], v[110:111], v[66:67] op_sel_hi:[1,0,1]
	v_pk_fma_f32 v[68:69], v[228:229], v[110:111], v[68:69] op_sel_hi:[1,0,1]
	v_pk_fma_f32 v[70:71], v[230:231], v[110:111], v[70:71] op_sel_hi:[1,0,1]
	v_pk_fma_f32 v[72:73], v[232:233], v[110:111], v[72:73] op_sel_hi:[1,0,1]
	v_pk_fma_f32 v[74:75], v[234:235], v[110:111], v[74:75] op_sel_hi:[1,0,1]
	v_pk_fma_f32 v[76:77], v[236:237], v[110:111], v[76:77] op_sel_hi:[1,0,1]
	v_pk_fma_f32 v[78:79], v[238:239], v[110:111], v[78:79] op_sel_hi:[1,0,1]
	ds_read_b128 v[208:211], v9 offset:7296
	ds_read_b128 v[212:215], v9 offset:7312
	ds_read_b128 v[216:219], v9 offset:7328
	ds_read_b128 v[220:223], v9 offset:7344
	s_waitcnt vmcnt(15) lgkmcnt(8)
	v_pk_fma_f32 v[64:65], v[176:177], v[112:113], v[64:65] op_sel_hi:[1,0,1]
	v_pk_fma_f32 v[66:67], v[178:179], v[112:113], v[66:67] op_sel_hi:[1,0,1]
	v_pk_fma_f32 v[68:69], v[180:181], v[112:113], v[68:69] op_sel_hi:[1,0,1]
	v_pk_fma_f32 v[70:71], v[182:183], v[112:113], v[70:71] op_sel_hi:[1,0,1]
	v_pk_fma_f32 v[72:73], v[184:185], v[112:113], v[72:73] op_sel_hi:[1,0,1]
	v_pk_fma_f32 v[74:75], v[186:187], v[112:113], v[74:75] op_sel_hi:[1,0,1]
	v_pk_fma_f32 v[76:77], v[188:189], v[112:113], v[76:77] op_sel_hi:[1,0,1]
	v_pk_fma_f32 v[78:79], v[190:191], v[112:113], v[78:79] op_sel_hi:[1,0,1]
	ds_read_b128 v[224:227], v9 offset:7360
	ds_read_b128 v[228:231], v9 offset:7376
	ds_read_b128 v[232:235], v9 offset:7392
	ds_read_b128 v[236:239], v9 offset:7408
	s_waitcnt vmcnt(14) lgkmcnt(8)
; #define LAS __attribute__((address_space(3)))
; __device__ __forceinline__ void ada_block(const Params& p, LAS unsigned char* lds, int blk, int tid) {
;     ...
;     for (int kk = 0; kk < 128; ++kk) {
;         const float wv = __builtin_nontemporal_load(wp + (size_t)kk * 3072);
;         const LAS f32x4* cp = (const LAS f32x4*)(cs + (w * 128 + kk) * 16);
;         a0 += cp[0] * wv; a1 += cp[1] * wv; a2 += cp[2] * wv; a3 += cp[3] * wv;
	v_pk_fma_f32 v[64:65], v[192:193], v[114:115], v[64:65] op_sel_hi:[1,0,1]
	v_pk_fma_f32 v[66:67], v[194:195], v[114:115], v[66:67] op_sel_hi:[1,0,1]
	v_pk_fma_f32 v[68:69], v[196:197], v[114:115], v[68:69] op_sel_hi:[1,0,1]
	v_pk_fma_f32 v[70:71], v[198:199], v[114:115], v[70:71] op_sel_hi:[1,0,1]
	v_pk_fma_f32 v[72:73], v[200:201], v[114:115], v[72:73] op_sel_hi:[1,0,1]
	v_pk_fma_f32 v[74:75], v[202:203], v[114:115], v[74:75] op_sel_hi:[1,0,1]
	v_pk_fma_f32 v[76:77], v[204:205], v[114:115], v[76:77] op_sel_hi:[1,0,1]
	v_pk_fma_f32 v[78:79], v[206:207], v[114:115], v[78:79] op_sel_hi:[1,0,1]
	ds_read_b128 v[176:179], v9 offset:7424
	ds_read_b128 v[180:183], v9 offset:7440
	ds_read_b128 v[184:187], v9 offset:7456
	ds_read_b128 v[188:191], v9 offset:7472
	s_waitcnt vmcnt(13) lgkmcnt(8)
	v_pk_fma_f32 v[64:65], v[208:209], v[116:117], v[64:65] op_sel_hi:[1,0,1]
	v_pk_fma_f32 v[66:67], v[210:211], v[116:117], v[66:67] op_sel_hi:[1,0,1]
	v_pk_fma_f32 v[68:69], v[212:213], v[116:117], v[68:69] op_sel_hi:[1,0,1]
	v_pk_fma_f32 v[70:71], v[214:215], v[116:117], v[70:71] op_sel_hi:[1,0,1]
	v_pk_fma_f32 v[72:73], v[216:217], v[116:117], v[72:73] op_sel_hi:[1,0,1]
	v_pk_fma_f32 v[74:75], v[218:219], v[116:117], v[74:75] op_sel_hi:[1,0,1]
	v_pk_fma_f32 v[76:77], v[220:221], v[116:117], v[76:77] op_sel_hi:[1,0,1]
	v_pk_fma_f32 v[78:79], v[222:223], v[116:117], v[78:79] op_sel_hi:[1,0,1]
	ds_read_b128 v[192:195], v9 offset:7488
	ds_read_b128 v[196:199], v9 offset:7504
	ds_read_b128 v[200:203], v9 offset:7520
	ds_read_b128 v[204:207], v9 offset:7536
	s_waitcnt vmcnt(12) lgkmcnt(8)
	v_pk_fma_f32 v[64:65], v[224:225], v[118:119], v[64:65] op_sel_hi:[1,0,1]
	v_pk_fma_f32 v[66:67], v[226:227], v[118:119], v[66:67] op_sel_hi:[1,0,1]
	v_pk_fma_f32 v[68:69], v[228:229], v[118:119], v[68:69] op_sel_hi:[1,0,1]
	v_pk_fma_f32 v[70:71], v[230:231], v[118:119], v[70:71] op_sel_hi:[1,0,1]
	v_pk_fma_f32 v[72:73], v[232:233], v[118:119], v[72:73] op_sel_hi:[1,0,1]
	v_pk_fma_f32 v[74:75], v[234:235], v[118:119], v[74:75] op_sel_hi:[1,0,1]
	v_pk_fma_f32 v[76:77], v[236:237], v[118:119], v[76:77] op_sel_hi:[1,0,1]
	v_pk_fma_f32 v[78:79], v[238:239], v[118:119], v[78:79] op_sel_hi:[1,0,1]
	ds_read_b128 v[208:211], v9 offset:7552
	ds_read_b128 v[212:215], v9 offset:7568
	ds_read_b128 v[216:219], v9 offset:7584
	ds_read_b128 v[220:223], v9 offset:7600
	s_waitcnt vmcnt(11) lgkmcnt(8)
	v_pk_fma_f32 v[64:65], v[176:177], v[120:121], v[64:65] op_sel_hi:[1,0,1]
	v_pk_fma_f32 v[66:67], v[178:179], v[120:121], v[66:67] op_sel_hi:[1,0,1]
	v_pk_fma_f32 v[68:69], v[180:181], v[120:121], v[68:69] op_sel_hi:[1,0,1]
	v_pk_fma_f32 v[70:71], v[182:183], v[120:121], v[70:71] op_sel_hi:[1,0,1]
	v_pk_fma_f32 v[72:73], v[184:185], v[120:121], v[72:73] op_sel_hi:[1,0,1]
	v_pk_fma_f32 v[74:75], v[186:187], v[120:121], v[74:75] op_sel_hi:[1,0,1]
	v_pk_fma_f32 v[76:77], v[188:189], v[120:121], v[76:77] op_sel_hi:[1,0,1]
	v_pk_fma_f32 v[78:79], v[190:191], v[120:121], v[78:79] op_sel_hi:[1,0,1]
	ds_read_b128 v[224:227], v9 offset:7616
	ds_read_b128 v[228:231], v9 offset:7632
	ds_read_b128 v[232:235], v9 offset:7648
	ds_read_b128 v[236:239], v9 offset:7664
	s_waitcnt vmcnt(10) lgkmcnt(8)
	v_pk_fma_f32 v[64:65], v[192:193], v[122:123], v[64:65] op_sel_hi:[1,0,1]
	v_pk_fma_f32 v[66:67], v[194:195], v[122:123], v[66:67] op_sel_hi:[1,0,1]
	v_pk_fma_f32 v[68:69], v[196:197], v[122:123], v[68:69] op_sel_hi:[1,0,1]
	v_pk_fma_f32 v[70:71], v[198:199], v[122:123], v[70:71] op_sel_hi:[1,0,1]
	v_pk_fma_f32 v[72:73], v[200:201], v[122:123], v[72:73] op_sel_hi:[1,0,1]
	v_pk_fma_f32 v[74:75], v[202:203], v[122:123], v[74:75] op_sel_hi:[1,0,1]
	v_pk_fma_f32 v[76:77], v[204:205], v[122:123], v[76:77] op_sel_hi:[1,0,1]
	v_pk_fma_f32 v[78:79], v[206:207], v[122:123], v[78:79] op_sel_hi:[1,0,1]
	ds_read_b128 v[176:179], v9 offset:7680
	ds_read_b128 v[180:183], v9 offset:7696
	ds_read_b128 v[184:187], v9 offset:7712
	ds_read_b128 v[188:191], v9 offset:7728
	s_waitcnt vmcnt(9) lgkmcnt(8)
	v_pk_fma_f32 v[64:65], v[208:209], v[124:125], v[64:65] op_sel_hi:[1,0,1]
	v_pk_fma_f32 v[66:67], v[210:211], v[124:125], v[66:67] op_sel_hi:[1,0,1]
	v_pk_fma_f32 v[68:69], v[212:213], v[124:125], v[68:69] op_sel_hi:[1,0,1]
	v_pk_fma_f32 v[70:71], v[214:215], v[124:125], v[70:71] op_sel_hi:[1,0,1]
	v_pk_fma_f32 v[72:73], v[216:217], v[124:125], v[72:73] op_sel_hi:[1,0,1]
	v_pk_fma_f32 v[74:75], v[218:219], v[124:125], v[74:75] op_sel_hi:[1,0,1]
	v_pk_fma_f32 v[76:77], v[220:221], v[124:125], v[76:77] op_sel_hi:[1,0,1]
	v_pk_fma_f32 v[78:79], v[222:223], v[124:125], v[78:79] op_sel_hi:[1,0,1]
	ds_read_b128 v[192:195], v9 offset:7744
	ds_read_b128 v[196:199], v9 offset:7760
	ds_read_b128 v[200:203], v9 offset:7776
	ds_read_b128 v[204:207], v9 offset:7792
	s_waitcnt vmcnt(8) lgkmcnt(8)
	v_pk_fma_f32 v[64:65], v[224:225], v[126:127], v[64:65] op_sel_hi:[1,0,1]
	v_pk_fma_f32 v[66:67], v[226:227], v[126:127], v[66:67] op_sel_hi:[1,0,1]
	v_pk_fma_f32 v[68:69], v[228:229], v[126:127], v[68:69] op_sel_hi:[1,0,1]
	v_pk_fma_f32 v[70:71], v[230:231], v[126:127], v[70:71] op_sel_hi:[1,0,1]
	v_pk_fma_f32 v[72:73], v[232:233], v[126:127], v[72:73] op_sel_hi:[1,0,1]
	v_pk_fma_f32 v[74:75], v[234:235], v[126:127], v[74:75] op_sel_hi:[1,0,1]
	v_pk_fma_f32 v[76:77], v[236:237], v[126:127], v[76:77] op_sel_hi:[1,0,1]
	v_pk_fma_f32 v[78:79], v[238:239], v[126:127], v[78:79] op_sel_hi:[1,0,1]
	ds_read_b128 v[208:211], v9 offset:7808
	ds_read_b128 v[212:215], v9 offset:7824
	ds_read_b128 v[216:219], v9 offset:7840
	ds_read_b128 v[220:223], v9 offset:7856
	s_waitcnt vmcnt(7) lgkmcnt(8)
; #define LAS __attribute__((address_space(3)))
; __device__ __forceinline__ void ada_block(const Params& p, LAS unsigned char* lds, int blk, int tid) {
;     ...
;     for (int kk = 0; kk < 128; ++kk) {
;         const float wv = __builtin_nontemporal_load(wp + (size_t)kk * 3072);
;         const LAS f32x4* cp = (const LAS f32x4*)(cs + (w * 128 + kk) * 16);
;         a0 += cp[0] * wv; a1 += cp[1] * wv; a2 += cp[2] * wv; a3 += cp[3] * wv;
;     }
; #pragma unroll
;     for (int j = 0; j < 4; ++j) { red[(w * 16 + j) * 64 + lane] = a0[j]; red[(w * 16 + 4 + j) * 64 + lane] = a1[j]; red[(w * 16 + 8 + j) * 64 + lane] = a2[j]; red[(w * 16 + 12 + j) * 64 + lane] = a3[j]; }
;     __syncthreads();
	v_pk_fma_f32 v[64:65], v[176:177], v[128:129], v[64:65] op_sel_hi:[1,0,1]
	v_pk_fma_f32 v[66:67], v[178:179], v[128:129], v[66:67] op_sel_hi:[1,0,1]
	v_pk_fma_f32 v[68:69], v[180:181], v[128:129], v[68:69] op_sel_hi:[1,0,1]
	v_pk_fma_f32 v[70:71], v[182:183], v[128:129], v[70:71] op_sel_hi:[1,0,1]
	v_pk_fma_f32 v[72:73], v[184:185], v[128:129], v[72:73] op_sel_hi:[1,0,1]
	v_pk_fma_f32 v[74:75], v[186:187], v[128:129], v[74:75] op_sel_hi:[1,0,1]
	v_pk_fma_f32 v[76:77], v[188:189], v[128:129], v[76:77] op_sel_hi:[1,0,1]
	v_pk_fma_f32 v[78:79], v[190:191], v[128:129], v[78:79] op_sel_hi:[1,0,1]
	ds_read_b128 v[224:227], v9 offset:7872
	ds_read_b128 v[228:231], v9 offset:7888
	ds_read_b128 v[232:235], v9 offset:7904
	ds_read_b128 v[236:239], v9 offset:7920
	s_waitcnt vmcnt(6) lgkmcnt(8)
	v_pk_fma_f32 v[64:65], v[192:193], v[130:131], v[64:65] op_sel_hi:[1,0,1]
	v_pk_fma_f32 v[66:67], v[194:195], v[130:131], v[66:67] op_sel_hi:[1,0,1]
	v_pk_fma_f32 v[68:69], v[196:197], v[130:131], v[68:69] op_sel_hi:[1,0,1]
	v_pk_fma_f32 v[70:71], v[198:199], v[130:131], v[70:71] op_sel_hi:[1,0,1]
	v_pk_fma_f32 v[72:73], v[200:201], v[130:131], v[72:73] op_sel_hi:[1,0,1]
	v_pk_fma_f32 v[74:75], v[202:203], v[130:131], v[74:75] op_sel_hi:[1,0,1]
	v_pk_fma_f32 v[76:77], v[204:205], v[130:131], v[76:77] op_sel_hi:[1,0,1]
	v_pk_fma_f32 v[78:79], v[206:207], v[130:131], v[78:79] op_sel_hi:[1,0,1]
	ds_read_b128 v[176:179], v9 offset:7936
	ds_read_b128 v[180:183], v9 offset:7952
	ds_read_b128 v[184:187], v9 offset:7968
	ds_read_b128 v[188:191], v9 offset:7984
	s_waitcnt vmcnt(5) lgkmcnt(8)
	v_pk_fma_f32 v[64:65], v[208:209], v[132:133], v[64:65] op_sel_hi:[1,0,1]
	v_pk_fma_f32 v[66:67], v[210:211], v[132:133], v[66:67] op_sel_hi:[1,0,1]
	v_pk_fma_f32 v[68:69], v[212:213], v[132:133], v[68:69] op_sel_hi:[1,0,1]
	v_pk_fma_f32 v[70:71], v[214:215], v[132:133], v[70:71] op_sel_hi:[1,0,1]
	v_pk_fma_f32 v[72:73], v[216:217], v[132:133], v[72:73] op_sel_hi:[1,0,1]
	v_pk_fma_f32 v[74:75], v[218:219], v[132:133], v[74:75] op_sel_hi:[1,0,1]
	v_pk_fma_f32 v[76:77], v[220:221], v[132:133], v[76:77] op_sel_hi:[1,0,1]
	v_pk_fma_f32 v[78:79], v[222:223], v[132:133], v[78:79] op_sel_hi:[1,0,1]
	ds_read_b128 v[192:195], v9 offset:8000
	ds_read_b128 v[196:199], v9 offset:8016
	ds_read_b128 v[200:203], v9 offset:8032
	ds_read_b128 v[204:207], v9 offset:8048
	s_waitcnt vmcnt(4) lgkmcnt(8)
	v_pk_fma_f32 v[64:65], v[224:225], v[134:135], v[64:65] op_sel_hi:[1,0,1]
	v_pk_fma_f32 v[66:67], v[226:227], v[134:135], v[66:67] op_sel_hi:[1,0,1]
	v_pk_fma_f32 v[68:69], v[228:229], v[134:135], v[68:69] op_sel_hi:[1,0,1]
	v_pk_fma_f32 v[70:71], v[230:231], v[134:135], v[70:71] op_sel_hi:[1,0,1]
	v_pk_fma_f32 v[72:73], v[232:233], v[134:135], v[72:73] op_sel_hi:[1,0,1]
	v_pk_fma_f32 v[74:75], v[234:235], v[134:135], v[74:75] op_sel_hi:[1,0,1]
	v_pk_fma_f32 v[76:77], v[236:237], v[134:135], v[76:77] op_sel_hi:[1,0,1]
	v_pk_fma_f32 v[78:79], v[238:239], v[134:135], v[78:79] op_sel_hi:[1,0,1]
	ds_read_b128 v[208:211], v9 offset:8064
	ds_read_b128 v[212:215], v9 offset:8080
	ds_read_b128 v[216:219], v9 offset:8096
	ds_read_b128 v[220:223], v9 offset:8112
	s_waitcnt vmcnt(3) lgkmcnt(8)
	v_pk_fma_f32 v[64:65], v[176:177], v[136:137], v[64:65] op_sel_hi:[1,0,1]
	v_pk_fma_f32 v[66:67], v[178:179], v[136:137], v[66:67] op_sel_hi:[1,0,1]
	v_pk_fma_f32 v[68:69], v[180:181], v[136:137], v[68:69] op_sel_hi:[1,0,1]
	v_pk_fma_f32 v[70:71], v[182:183], v[136:137], v[70:71] op_sel_hi:[1,0,1]
	v_pk_fma_f32 v[72:73], v[184:185], v[136:137], v[72:73] op_sel_hi:[1,0,1]
	v_pk_fma_f32 v[74:75], v[186:187], v[136:137], v[74:75] op_sel_hi:[1,0,1]
	v_pk_fma_f32 v[76:77], v[188:189], v[136:137], v[76:77] op_sel_hi:[1,0,1]
	v_pk_fma_f32 v[78:79], v[190:191], v[136:137], v[78:79] op_sel_hi:[1,0,1]
	ds_read_b128 v[224:227], v9 offset:8128
	ds_read_b128 v[228:231], v9 offset:8144
	ds_read_b128 v[232:235], v9 offset:8160
	ds_read_b128 v[236:239], v9 offset:8176
	s_waitcnt vmcnt(2) lgkmcnt(8)
	v_pk_fma_f32 v[64:65], v[192:193], v[138:139], v[64:65] op_sel_hi:[1,0,1]
	v_pk_fma_f32 v[66:67], v[194:195], v[138:139], v[66:67] op_sel_hi:[1,0,1]
	v_pk_fma_f32 v[68:69], v[196:197], v[138:139], v[68:69] op_sel_hi:[1,0,1]
	v_pk_fma_f32 v[70:71], v[198:199], v[138:139], v[70:71] op_sel_hi:[1,0,1]
	v_pk_fma_f32 v[72:73], v[200:201], v[138:139], v[72:73] op_sel_hi:[1,0,1]
	v_pk_fma_f32 v[74:75], v[202:203], v[138:139], v[74:75] op_sel_hi:[1,0,1]
	v_pk_fma_f32 v[76:77], v[204:205], v[138:139], v[76:77] op_sel_hi:[1,0,1]
	v_pk_fma_f32 v[78:79], v[206:207], v[138:139], v[78:79] op_sel_hi:[1,0,1]
	s_waitcnt vmcnt(1) lgkmcnt(4)
	v_pk_fma_f32 v[64:65], v[208:209], v[140:141], v[64:65] op_sel_hi:[1,0,1]
	v_pk_fma_f32 v[66:67], v[210:211], v[140:141], v[66:67] op_sel_hi:[1,0,1]
	v_pk_fma_f32 v[68:69], v[212:213], v[140:141], v[68:69] op_sel_hi:[1,0,1]
	v_pk_fma_f32 v[70:71], v[214:215], v[140:141], v[70:71] op_sel_hi:[1,0,1]
	v_pk_fma_f32 v[72:73], v[216:217], v[140:141], v[72:73] op_sel_hi:[1,0,1]
	v_pk_fma_f32 v[74:75], v[218:219], v[140:141], v[74:75] op_sel_hi:[1,0,1]
	v_pk_fma_f32 v[76:77], v[220:221], v[140:141], v[76:77] op_sel_hi:[1,0,1]
	v_pk_fma_f32 v[78:79], v[222:223], v[140:141], v[78:79] op_sel_hi:[1,0,1]
	s_waitcnt vmcnt(0) lgkmcnt(0)
	v_pk_fma_f32 v[64:65], v[224:225], v[142:143], v[64:65] op_sel_hi:[1,0,1]
	v_pk_fma_f32 v[66:67], v[226:227], v[142:143], v[66:67] op_sel_hi:[1,0,1]
	v_pk_fma_f32 v[68:69], v[228:229], v[142:143], v[68:69] op_sel_hi:[1,0,1]
	v_pk_fma_f32 v[70:71], v[230:231], v[142:143], v[70:71] op_sel_hi:[1,0,1]
	v_pk_fma_f32 v[72:73], v[232:233], v[142:143], v[72:73] op_sel_hi:[1,0,1]
	v_pk_fma_f32 v[74:75], v[234:235], v[142:143], v[74:75] op_sel_hi:[1,0,1]
	v_pk_fma_f32 v[76:77], v[236:237], v[142:143], v[76:77] op_sel_hi:[1,0,1]
	v_pk_fma_f32 v[78:79], v[238:239], v[142:143], v[78:79] op_sel_hi:[1,0,1]
	v_mov_b32_e32 v28, v64
	v_mov_b32_e32 v29, v65
	v_mov_b32_e32 v30, v66
	v_mov_b32_e32 v31, v67
	v_mov_b32_e32 v22, v68
	v_mov_b32_e32 v23, v69
	v_mov_b32_e32 v16, v70
	v_mov_b32_e32 v17, v71
	v_mov_b32_e32 v20, v72
	v_mov_b32_e32 v21, v73
	v_mov_b32_e32 v14, v74
	v_mov_b32_e32 v15, v75
	v_mov_b32_e32 v18, v76
	v_mov_b32_e32 v19, v77
	v_mov_b32_e32 v12, v78
	v_mov_b32_e32 v13, v79
	s_add_i32 s8, 0, 0x10000
	v_lshl_add_u32 v6, v0, 2, s8
	v_mov_b32_e32 v4, s82
	v_mov_b32_e32 v5, s83
	v_lshl_add_u32 v7, v1, 12, v6
	v_mul_u32_u24_e32 v1, 0xc00, v1
	v_lshl_add_u64 v[2:3], v[2:3], 2, v[4:5]
	v_add3_u32 v4, v1, s10, v0
	s_mov_b64 s[8:9], 0
	s_movk_i32 s10, 0x1ff
	v_mov_b32_e32 v1, v170
	ds_write2st64_b32 v7, v28, v29 offset1:1
	ds_write2st64_b32 v7, v22, v23 offset0:4 offset1:5
	ds_write2st64_b32 v7, v20, v21 offset0:8 offset1:9
	ds_write2st64_b32 v7, v18, v19 offset0:12 offset1:13
	ds_write2st64_b32 v7, v30, v31 offset0:2 offset1:3
	ds_write2st64_b32 v7, v16, v17 offset0:6 offset1:7
	ds_write2st64_b32 v7, v14, v15 offset0:10 offset1:11
	ds_write2st64_b32 v7, v12, v13 offset0:14 offset1:15
	s_waitcnt lgkmcnt(0)
	s_barrier
